# v18 + NSA window/selected branch epilogues: 64 serialized LDS read-modify-write round trips replaced by 64 batched LDS reads into free VGPRs + one wait
# speedup vs baseline: 1.0008x; 1.0008x over previous
.LBB0_1774:
	s_or_b64 exec, exec, s[10:11]
	s_waitcnt vmcnt(1)
	v_ashrrev_i32_e32 v2, 5, v16
	s_waitcnt lgkmcnt(0)
	s_waitcnt vmcnt(0)
	v_lshl_add_u32 v4, v2, 4, s33
	ds_read_b128 v[82:85], v4
	ds_read_b128 v[12:15], v4 offset:32
	ds_read_b128 v[8:11], v4 offset:64
	ds_read_b128 v[4:7], v4 offset:96
	s_waitcnt lgkmcnt(0)
	v_lshlrev_b32_e32 v17, 1, v16
	v_and_b32_e32 v16, 1, v16
	v_lshlrev_b32_e32 v2, 10, v2
	v_and_b32_e32 v17, 60, v17
	v_cmp_eq_u32_e32 vcc, 0, v16
	s_waitcnt lgkmcnt(3)
	v_mul_f32_e32 v16, v66, v82
	v_add3_u32 v2, s83, v2, v17
	ds_read_b32 v195, v2
	ds_read_b32 v196, v2 offset:64
	ds_read_b32 v197, v2 offset:128
	ds_read_b32 v198, v2 offset:192
	ds_read_b32 v199, v2 offset:256
	ds_read_b32 v200, v2 offset:320
	ds_read_b32 v201, v2 offset:384
	ds_read_b32 v202, v2 offset:448
	ds_read_b32 v203, v2 offset:512
	ds_read_b32 v204, v2 offset:576
	ds_read_b32 v205, v2 offset:640
	ds_read_b32 v206, v2 offset:704
	ds_read_b32 v207, v2 offset:768
	ds_read_b32 v208, v2 offset:832
	ds_read_b32 v209, v2 offset:896
	ds_read_b32 v210, v2 offset:960
	ds_read_b32 v211, v2 offset:2048
	ds_read_b32 v212, v2 offset:2112
	ds_read_b32 v213, v2 offset:2176
	ds_read_b32 v214, v2 offset:2240
	ds_read_b32 v215, v2 offset:2304
	ds_read_b32 v216, v2 offset:2368
	ds_read_b32 v217, v2 offset:2432
	ds_read_b32 v218, v2 offset:2496
	ds_read_b32 v219, v2 offset:2560
	ds_read_b32 v220, v2 offset:2624
	ds_read_b32 v221, v2 offset:2688
	ds_read_b32 v222, v2 offset:2752
	ds_read_b32 v223, v2 offset:2816
	ds_read_b32 v224, v2 offset:2880
	ds_read_b32 v225, v2 offset:2944
	ds_read_b32 v226, v2 offset:3008
	ds_read_b32 v227, v2 offset:4096
	ds_read_b32 v228, v2 offset:4160
	ds_read_b32 v229, v2 offset:4224
	ds_read_b32 v230, v2 offset:4288
	ds_read_b32 v231, v2 offset:4352
	ds_read_b32 v232, v2 offset:4416
	ds_read_b32 v233, v2 offset:4480
	ds_read_b32 v234, v2 offset:4544
	ds_read_b32 v235, v2 offset:4608
	ds_read_b32 v236, v2 offset:4672
	ds_read_b32 v237, v2 offset:4736
	ds_read_b32 v238, v2 offset:4800
	ds_read_b32 v239, v2 offset:4864
	ds_read_b32 v92, v2 offset:4928
	ds_read_b32 v93, v2 offset:4992
	ds_read_b32 v94, v2 offset:5056
	ds_read_b32 v95, v2 offset:6144
	ds_read_b32 v96, v2 offset:6208
	ds_read_b32 v97, v2 offset:6272
	ds_read_b32 v98, v2 offset:6336
	ds_read_b32 v99, v2 offset:6400
	ds_read_b32 v100, v2 offset:6464
	ds_read_b32 v101, v2 offset:6528
	ds_read_b32 v102, v2 offset:6592
	ds_read_b32 v103, v2 offset:6656
	ds_read_b32 v104, v2 offset:6720
	ds_read_b32 v105, v2 offset:6784
	ds_read_b32 v106, v2 offset:6848
	ds_read_b32 v107, v2 offset:6912
	ds_read_b32 v108, v2 offset:6976
	ds_read_b32 v109, v2 offset:7040
	ds_read_b32 v110, v2 offset:7104
	s_waitcnt lgkmcnt(0)
	s_nop 0
	v_mov_b32_dpp v17, v16 quad_perm:[1,0,3,2] row_mask:0xf bank_mask:0xf bound_ctrl:1
	s_and_saveexec_b64 s[10:11], vcc
	s_cbranch_execz .LBB0_1776
	v_mov_b32_e32 v66, v195
	v_lshlrev_b32_e32 v86, 16, v66
	v_and_b32_e32 v66, 0xffff0000, v66
	v_add_f32_e32 v16, v16, v86
	v_add_f32_e32 v17, v17, v66
	v_cvt_pk_bf16_f32 v16, v16, v17
	ds_write_b32 v2, v16
.LBB0_1776:
	s_or_b64 exec, exec, s[10:11]
	v_mul_f32_e32 v16, v50, v82
	s_nop 1
	v_mov_b32_dpp v17, v16 quad_perm:[1,0,3,2] row_mask:0xf bank_mask:0xf bound_ctrl:1
	s_and_saveexec_b64 s[10:11], vcc
	s_cbranch_execz .LBB0_1778
	v_mov_b32_e32 v50, v196
	v_lshlrev_b32_e32 v66, 16, v50
	v_and_b32_e32 v50, 0xffff0000, v50
	v_add_f32_e32 v16, v16, v66
	v_add_f32_e32 v17, v17, v50
	v_cvt_pk_bf16_f32 v16, v16, v17
	ds_write_b32 v2, v16 offset:64
.LBB0_1778:
	s_or_b64 exec, exec, s[10:11]
	v_mul_f32_e32 v16, v34, v82
	s_nop 1
	v_mov_b32_dpp v17, v16 quad_perm:[1,0,3,2] row_mask:0xf bank_mask:0xf bound_ctrl:1
	s_and_saveexec_b64 s[10:11], vcc
	s_cbranch_execz .LBB0_1780
	v_mov_b32_e32 v34, v197
	v_lshlrev_b32_e32 v50, 16, v34
	v_and_b32_e32 v34, 0xffff0000, v34
	v_add_f32_e32 v16, v16, v50
	v_add_f32_e32 v17, v17, v34
	v_cvt_pk_bf16_f32 v16, v16, v17
	ds_write_b32 v2, v16 offset:128
.LBB0_1780:
	s_or_b64 exec, exec, s[10:11]
	v_mul_f32_e32 v16, v18, v82
	s_nop 1
	v_mov_b32_dpp v17, v16 quad_perm:[1,0,3,2] row_mask:0xf bank_mask:0xf bound_ctrl:1
	s_and_saveexec_b64 s[10:11], vcc
	s_cbranch_execz .LBB0_1782
	v_mov_b32_e32 v18, v198
	v_lshlrev_b32_e32 v34, 16, v18
	v_and_b32_e32 v18, 0xffff0000, v18
	v_add_f32_e32 v16, v16, v34
	v_add_f32_e32 v17, v17, v18
	v_cvt_pk_bf16_f32 v16, v16, v17
	ds_write_b32 v2, v16 offset:192
.LBB0_1782:
	s_or_b64 exec, exec, s[10:11]
	v_mul_f32_e32 v16, v67, v83
	s_nop 1
	v_mov_b32_dpp v17, v16 quad_perm:[1,0,3,2] row_mask:0xf bank_mask:0xf bound_ctrl:1
	s_and_saveexec_b64 s[10:11], vcc
	s_cbranch_execz .LBB0_1784
	v_mov_b32_e32 v18, v199
	v_lshlrev_b32_e32 v34, 16, v18
	v_and_b32_e32 v18, 0xffff0000, v18
	v_add_f32_e32 v16, v16, v34
	v_add_f32_e32 v17, v17, v18
	v_cvt_pk_bf16_f32 v16, v16, v17
	ds_write_b32 v2, v16 offset:256
.LBB0_1784:
	s_or_b64 exec, exec, s[10:11]
	v_mul_f32_e32 v16, v51, v83
	s_nop 1
	v_mov_b32_dpp v17, v16 quad_perm:[1,0,3,2] row_mask:0xf bank_mask:0xf bound_ctrl:1
	s_and_saveexec_b64 s[10:11], vcc
	s_cbranch_execz .LBB0_1786
	v_mov_b32_e32 v18, v200
	v_lshlrev_b32_e32 v34, 16, v18
	v_and_b32_e32 v18, 0xffff0000, v18
	v_add_f32_e32 v16, v16, v34
	v_add_f32_e32 v17, v17, v18
	v_cvt_pk_bf16_f32 v16, v16, v17
	ds_write_b32 v2, v16 offset:320
.LBB0_1786:
	s_or_b64 exec, exec, s[10:11]
	v_mul_f32_e32 v16, v35, v83
	s_nop 1
	v_mov_b32_dpp v17, v16 quad_perm:[1,0,3,2] row_mask:0xf bank_mask:0xf bound_ctrl:1
	s_and_saveexec_b64 s[10:11], vcc
	s_cbranch_execz .LBB0_1788
	v_mov_b32_e32 v18, v201
	v_lshlrev_b32_e32 v34, 16, v18
	v_and_b32_e32 v18, 0xffff0000, v18
	v_add_f32_e32 v16, v16, v34
	v_add_f32_e32 v17, v17, v18
	v_cvt_pk_bf16_f32 v16, v16, v17
	ds_write_b32 v2, v16 offset:384
.LBB0_1788:
	s_or_b64 exec, exec, s[10:11]
	v_mul_f32_e32 v16, v19, v83
	s_nop 1
	v_mov_b32_dpp v17, v16 quad_perm:[1,0,3,2] row_mask:0xf bank_mask:0xf bound_ctrl:1
	s_and_saveexec_b64 s[10:11], vcc
	s_cbranch_execz .LBB0_1790
	v_mov_b32_e32 v18, v202
	v_lshlrev_b32_e32 v19, 16, v18
	v_and_b32_e32 v18, 0xffff0000, v18
	v_add_f32_e32 v16, v16, v19
	v_add_f32_e32 v17, v17, v18
	v_cvt_pk_bf16_f32 v16, v16, v17
	ds_write_b32 v2, v16 offset:448
.LBB0_1790:
	s_or_b64 exec, exec, s[10:11]
	v_mul_f32_e32 v16, v68, v84
	s_nop 1
	v_mov_b32_dpp v17, v16 quad_perm:[1,0,3,2] row_mask:0xf bank_mask:0xf bound_ctrl:1
	s_and_saveexec_b64 s[10:11], vcc
	s_cbranch_execz .LBB0_1792
	v_mov_b32_e32 v18, v203
	v_lshlrev_b32_e32 v19, 16, v18
	v_and_b32_e32 v18, 0xffff0000, v18
	v_add_f32_e32 v16, v16, v19
	v_add_f32_e32 v17, v17, v18
	v_cvt_pk_bf16_f32 v16, v16, v17
	ds_write_b32 v2, v16 offset:512
.LBB0_1792:
	s_or_b64 exec, exec, s[10:11]
	v_mul_f32_e32 v16, v52, v84
	s_nop 1
	v_mov_b32_dpp v17, v16 quad_perm:[1,0,3,2] row_mask:0xf bank_mask:0xf bound_ctrl:1
	s_and_saveexec_b64 s[10:11], vcc
	s_cbranch_execz .LBB0_1794
	v_mov_b32_e32 v18, v204
	v_lshlrev_b32_e32 v19, 16, v18
	v_and_b32_e32 v18, 0xffff0000, v18
	v_add_f32_e32 v16, v16, v19
	v_add_f32_e32 v17, v17, v18
	v_cvt_pk_bf16_f32 v16, v16, v17
	ds_write_b32 v2, v16 offset:576
.LBB0_1794:
	s_or_b64 exec, exec, s[10:11]
	v_mul_f32_e32 v16, v36, v84
	s_nop 1
	v_mov_b32_dpp v17, v16 quad_perm:[1,0,3,2] row_mask:0xf bank_mask:0xf bound_ctrl:1
	s_and_saveexec_b64 s[10:11], vcc
	s_cbranch_execz .LBB0_1796
	v_mov_b32_e32 v18, v205
	v_lshlrev_b32_e32 v19, 16, v18
	v_and_b32_e32 v18, 0xffff0000, v18
	v_add_f32_e32 v16, v16, v19
	v_add_f32_e32 v17, v17, v18
	v_cvt_pk_bf16_f32 v16, v16, v17
	ds_write_b32 v2, v16 offset:640
.LBB0_1796:
	s_or_b64 exec, exec, s[10:11]
	v_mul_f32_e32 v16, v20, v84
	s_nop 1
	v_mov_b32_dpp v17, v16 quad_perm:[1,0,3,2] row_mask:0xf bank_mask:0xf bound_ctrl:1
	s_and_saveexec_b64 s[10:11], vcc
	s_cbranch_execz .LBB0_1798
	v_mov_b32_e32 v18, v206
	v_lshlrev_b32_e32 v19, 16, v18
	v_and_b32_e32 v18, 0xffff0000, v18
	v_add_f32_e32 v16, v16, v19
	v_add_f32_e32 v17, v17, v18
	v_cvt_pk_bf16_f32 v16, v16, v17
	ds_write_b32 v2, v16 offset:704
.LBB0_1798:
	s_or_b64 exec, exec, s[10:11]
	v_mul_f32_e32 v16, v69, v85
	s_nop 1
	v_mov_b32_dpp v17, v16 quad_perm:[1,0,3,2] row_mask:0xf bank_mask:0xf bound_ctrl:1
	s_and_saveexec_b64 s[10:11], vcc
	s_cbranch_execz .LBB0_1800
	v_mov_b32_e32 v18, v207
	v_lshlrev_b32_e32 v19, 16, v18
	v_and_b32_e32 v18, 0xffff0000, v18
	v_add_f32_e32 v16, v16, v19
	v_add_f32_e32 v17, v17, v18
	v_cvt_pk_bf16_f32 v16, v16, v17
	ds_write_b32 v2, v16 offset:768
.LBB0_1800:
	s_or_b64 exec, exec, s[10:11]
	v_mul_f32_e32 v16, v53, v85
	s_nop 1
	v_mov_b32_dpp v17, v16 quad_perm:[1,0,3,2] row_mask:0xf bank_mask:0xf bound_ctrl:1
	s_and_saveexec_b64 s[10:11], vcc
	s_cbranch_execz .LBB0_1802
	v_mov_b32_e32 v18, v208
	v_lshlrev_b32_e32 v19, 16, v18
	v_and_b32_e32 v18, 0xffff0000, v18
	v_add_f32_e32 v16, v16, v19
	v_add_f32_e32 v17, v17, v18
	v_cvt_pk_bf16_f32 v16, v16, v17
	ds_write_b32 v2, v16 offset:832
.LBB0_1802:
	s_or_b64 exec, exec, s[10:11]
	v_mul_f32_e32 v16, v37, v85
	s_nop 1
	v_mov_b32_dpp v17, v16 quad_perm:[1,0,3,2] row_mask:0xf bank_mask:0xf bound_ctrl:1
	s_and_saveexec_b64 s[10:11], vcc
	s_cbranch_execz .LBB0_1804
	v_mov_b32_e32 v18, v209
	v_lshlrev_b32_e32 v19, 16, v18
	v_and_b32_e32 v18, 0xffff0000, v18
	v_add_f32_e32 v16, v16, v19
	v_add_f32_e32 v17, v17, v18
	v_cvt_pk_bf16_f32 v16, v16, v17
	ds_write_b32 v2, v16 offset:896
.LBB0_1804:
	s_or_b64 exec, exec, s[10:11]
	v_mul_f32_e32 v16, v21, v85
	s_nop 1
	v_mov_b32_dpp v17, v16 quad_perm:[1,0,3,2] row_mask:0xf bank_mask:0xf bound_ctrl:1
	s_and_saveexec_b64 s[10:11], vcc
	s_cbranch_execz .LBB0_1806
	v_mov_b32_e32 v18, v210
	v_lshlrev_b32_e32 v19, 16, v18
	v_and_b32_e32 v18, 0xffff0000, v18
	v_add_f32_e32 v16, v16, v19
	v_add_f32_e32 v17, v17, v18
	v_cvt_pk_bf16_f32 v16, v16, v17
	ds_write_b32 v2, v16 offset:960
.LBB0_1806:
	s_or_b64 exec, exec, s[10:11]
	s_waitcnt lgkmcnt(2)
	v_mul_f32_e32 v16, v70, v12
	s_nop 1
	v_mov_b32_dpp v17, v16 quad_perm:[1,0,3,2] row_mask:0xf bank_mask:0xf bound_ctrl:1
	s_and_saveexec_b64 s[10:11], vcc
	s_cbranch_execz .LBB0_1808
	v_mov_b32_e32 v18, v211
	v_lshlrev_b32_e32 v19, 16, v18
	v_and_b32_e32 v18, 0xffff0000, v18
	v_add_f32_e32 v16, v16, v19
	v_add_f32_e32 v17, v17, v18
	v_cvt_pk_bf16_f32 v16, v16, v17
	ds_write_b32 v2, v16 offset:2048
.LBB0_1808:
	s_or_b64 exec, exec, s[10:11]
	v_mul_f32_e32 v16, v54, v12
	s_nop 1
	v_mov_b32_dpp v17, v16 quad_perm:[1,0,3,2] row_mask:0xf bank_mask:0xf bound_ctrl:1
	s_and_saveexec_b64 s[10:11], vcc
	s_cbranch_execz .LBB0_1810
	v_mov_b32_e32 v18, v212
	v_lshlrev_b32_e32 v19, 16, v18
	v_and_b32_e32 v18, 0xffff0000, v18
	v_add_f32_e32 v16, v16, v19
	v_add_f32_e32 v17, v17, v18
	v_cvt_pk_bf16_f32 v16, v16, v17
	ds_write_b32 v2, v16 offset:2112
.LBB0_1810:
	s_or_b64 exec, exec, s[10:11]
	v_mul_f32_e32 v16, v38, v12
	s_nop 1
	v_mov_b32_dpp v17, v16 quad_perm:[1,0,3,2] row_mask:0xf bank_mask:0xf bound_ctrl:1
	s_and_saveexec_b64 s[10:11], vcc
	s_cbranch_execz .LBB0_1812
	v_mov_b32_e32 v18, v213
	v_lshlrev_b32_e32 v19, 16, v18
	v_and_b32_e32 v18, 0xffff0000, v18
	v_add_f32_e32 v16, v16, v19
	v_add_f32_e32 v17, v17, v18
	v_cvt_pk_bf16_f32 v16, v16, v17
	ds_write_b32 v2, v16 offset:2176
.LBB0_1812:
	s_or_b64 exec, exec, s[10:11]
	v_mul_f32_e32 v12, v22, v12
	s_nop 1
	v_mov_b32_dpp v16, v12 quad_perm:[1,0,3,2] row_mask:0xf bank_mask:0xf bound_ctrl:1
	s_and_saveexec_b64 s[10:11], vcc
	s_cbranch_execz .LBB0_1814
	v_mov_b32_e32 v17, v214
	v_lshlrev_b32_e32 v18, 16, v17
	v_and_b32_e32 v17, 0xffff0000, v17
	v_add_f32_e32 v12, v12, v18
	v_add_f32_e32 v16, v16, v17
	v_cvt_pk_bf16_f32 v12, v12, v16
	ds_write_b32 v2, v12 offset:2240
.LBB0_1814:
	s_or_b64 exec, exec, s[10:11]
	v_mul_f32_e32 v12, v71, v13
	s_nop 1
	v_mov_b32_dpp v16, v12 quad_perm:[1,0,3,2] row_mask:0xf bank_mask:0xf bound_ctrl:1
	s_and_saveexec_b64 s[10:11], vcc
	s_cbranch_execz .LBB0_1816
	v_mov_b32_e32 v17, v215
	v_lshlrev_b32_e32 v18, 16, v17
	v_and_b32_e32 v17, 0xffff0000, v17
	v_add_f32_e32 v12, v12, v18
	v_add_f32_e32 v16, v16, v17
	v_cvt_pk_bf16_f32 v12, v12, v16
	ds_write_b32 v2, v12 offset:2304
.LBB0_1816:
	s_or_b64 exec, exec, s[10:11]
	v_mul_f32_e32 v12, v55, v13
	s_nop 1
	v_mov_b32_dpp v16, v12 quad_perm:[1,0,3,2] row_mask:0xf bank_mask:0xf bound_ctrl:1
	s_and_saveexec_b64 s[10:11], vcc
	s_cbranch_execz .LBB0_1818
	v_mov_b32_e32 v17, v216
	v_lshlrev_b32_e32 v18, 16, v17
	v_and_b32_e32 v17, 0xffff0000, v17
	v_add_f32_e32 v12, v12, v18
	v_add_f32_e32 v16, v16, v17
	v_cvt_pk_bf16_f32 v12, v12, v16
	ds_write_b32 v2, v12 offset:2368
.LBB0_1818:
	s_or_b64 exec, exec, s[10:11]
	v_mul_f32_e32 v12, v39, v13
	s_nop 1
	v_mov_b32_dpp v16, v12 quad_perm:[1,0,3,2] row_mask:0xf bank_mask:0xf bound_ctrl:1
	s_and_saveexec_b64 s[10:11], vcc
	s_cbranch_execz .LBB0_1820
	v_mov_b32_e32 v17, v217
	v_lshlrev_b32_e32 v18, 16, v17
	v_and_b32_e32 v17, 0xffff0000, v17
	v_add_f32_e32 v12, v12, v18
	v_add_f32_e32 v16, v16, v17
	v_cvt_pk_bf16_f32 v12, v12, v16
	ds_write_b32 v2, v12 offset:2432
.LBB0_1820:
	s_or_b64 exec, exec, s[10:11]
	v_mul_f32_e32 v12, v23, v13
	s_nop 1
	v_mov_b32_dpp v13, v12 quad_perm:[1,0,3,2] row_mask:0xf bank_mask:0xf bound_ctrl:1
	s_and_saveexec_b64 s[10:11], vcc
	s_cbranch_execz .LBB0_1822
	v_mov_b32_e32 v16, v218
	v_lshlrev_b32_e32 v17, 16, v16
	v_and_b32_e32 v16, 0xffff0000, v16
	v_add_f32_e32 v12, v12, v17
	v_add_f32_e32 v13, v13, v16
	v_cvt_pk_bf16_f32 v12, v12, v13
	ds_write_b32 v2, v12 offset:2496
.LBB0_1822:
	s_or_b64 exec, exec, s[10:11]
	v_mul_f32_e32 v12, v72, v14
	s_nop 1
	v_mov_b32_dpp v13, v12 quad_perm:[1,0,3,2] row_mask:0xf bank_mask:0xf bound_ctrl:1
	s_and_saveexec_b64 s[10:11], vcc
	s_cbranch_execz .LBB0_1824
	v_mov_b32_e32 v16, v219
	v_lshlrev_b32_e32 v17, 16, v16
	v_and_b32_e32 v16, 0xffff0000, v16
	v_add_f32_e32 v12, v12, v17
	v_add_f32_e32 v13, v13, v16
	v_cvt_pk_bf16_f32 v12, v12, v13
	ds_write_b32 v2, v12 offset:2560
.LBB0_1824:
	s_or_b64 exec, exec, s[10:11]
	v_mul_f32_e32 v12, v56, v14
	s_nop 1
	v_mov_b32_dpp v13, v12 quad_perm:[1,0,3,2] row_mask:0xf bank_mask:0xf bound_ctrl:1
	s_and_saveexec_b64 s[10:11], vcc
	s_cbranch_execz .LBB0_1826
	v_mov_b32_e32 v16, v220
	v_lshlrev_b32_e32 v17, 16, v16
	v_and_b32_e32 v16, 0xffff0000, v16
	v_add_f32_e32 v12, v12, v17
	v_add_f32_e32 v13, v13, v16
	v_cvt_pk_bf16_f32 v12, v12, v13
	ds_write_b32 v2, v12 offset:2624
.LBB0_1826:
	s_or_b64 exec, exec, s[10:11]
	v_mul_f32_e32 v12, v40, v14
	s_nop 1
	v_mov_b32_dpp v13, v12 quad_perm:[1,0,3,2] row_mask:0xf bank_mask:0xf bound_ctrl:1
	s_and_saveexec_b64 s[10:11], vcc
	s_cbranch_execz .LBB0_1828
	v_mov_b32_e32 v16, v221
	v_lshlrev_b32_e32 v17, 16, v16
	v_and_b32_e32 v16, 0xffff0000, v16
	v_add_f32_e32 v12, v12, v17
	v_add_f32_e32 v13, v13, v16
	v_cvt_pk_bf16_f32 v12, v12, v13
	ds_write_b32 v2, v12 offset:2688
.LBB0_1828:
	s_or_b64 exec, exec, s[10:11]
	v_mul_f32_e32 v12, v24, v14
	s_nop 1
	v_mov_b32_dpp v13, v12 quad_perm:[1,0,3,2] row_mask:0xf bank_mask:0xf bound_ctrl:1
	s_and_saveexec_b64 s[10:11], vcc
	s_cbranch_execz .LBB0_1830
	v_mov_b32_e32 v14, v222
	v_lshlrev_b32_e32 v16, 16, v14
	v_and_b32_e32 v14, 0xffff0000, v14
	v_add_f32_e32 v12, v12, v16
	v_add_f32_e32 v13, v13, v14
	v_cvt_pk_bf16_f32 v12, v12, v13
	ds_write_b32 v2, v12 offset:2752
.LBB0_1830:
	s_or_b64 exec, exec, s[10:11]
	v_mul_f32_e32 v12, v73, v15
	s_nop 1
	v_mov_b32_dpp v13, v12 quad_perm:[1,0,3,2] row_mask:0xf bank_mask:0xf bound_ctrl:1
	s_and_saveexec_b64 s[10:11], vcc
	s_cbranch_execz .LBB0_1832
	v_mov_b32_e32 v14, v223
	v_lshlrev_b32_e32 v16, 16, v14
	v_and_b32_e32 v14, 0xffff0000, v14
	v_add_f32_e32 v12, v12, v16
	v_add_f32_e32 v13, v13, v14
	v_cvt_pk_bf16_f32 v12, v12, v13
	ds_write_b32 v2, v12 offset:2816
.LBB0_1832:
	s_or_b64 exec, exec, s[10:11]
	v_mul_f32_e32 v12, v57, v15
	s_nop 1
	v_mov_b32_dpp v13, v12 quad_perm:[1,0,3,2] row_mask:0xf bank_mask:0xf bound_ctrl:1
	s_and_saveexec_b64 s[10:11], vcc
	s_cbranch_execz .LBB0_1834
	v_mov_b32_e32 v14, v224
	v_lshlrev_b32_e32 v16, 16, v14
	v_and_b32_e32 v14, 0xffff0000, v14
	v_add_f32_e32 v12, v12, v16
	v_add_f32_e32 v13, v13, v14
	v_cvt_pk_bf16_f32 v12, v12, v13
	ds_write_b32 v2, v12 offset:2880
.LBB0_1834:
	s_or_b64 exec, exec, s[10:11]
	v_mul_f32_e32 v12, v41, v15
	s_nop 1
	v_mov_b32_dpp v13, v12 quad_perm:[1,0,3,2] row_mask:0xf bank_mask:0xf bound_ctrl:1
	s_and_saveexec_b64 s[10:11], vcc
	s_cbranch_execz .LBB0_1836
	v_mov_b32_e32 v14, v225
	v_lshlrev_b32_e32 v16, 16, v14
	v_and_b32_e32 v14, 0xffff0000, v14
	v_add_f32_e32 v12, v12, v16
	v_add_f32_e32 v13, v13, v14
	v_cvt_pk_bf16_f32 v12, v12, v13
	ds_write_b32 v2, v12 offset:2944
.LBB0_1836:
	s_or_b64 exec, exec, s[10:11]
	v_mul_f32_e32 v12, v25, v15
	s_nop 1
	v_mov_b32_dpp v13, v12 quad_perm:[1,0,3,2] row_mask:0xf bank_mask:0xf bound_ctrl:1
	s_and_saveexec_b64 s[10:11], vcc
	s_cbranch_execz .LBB0_1838
	v_mov_b32_e32 v14, v226
	v_lshlrev_b32_e32 v15, 16, v14
	v_and_b32_e32 v14, 0xffff0000, v14
	v_add_f32_e32 v12, v12, v15
	v_add_f32_e32 v13, v13, v14
	v_cvt_pk_bf16_f32 v12, v12, v13
	ds_write_b32 v2, v12 offset:3008
.LBB0_1838:
	s_or_b64 exec, exec, s[10:11]
	s_waitcnt lgkmcnt(1)
	v_mul_f32_e32 v12, v74, v8
	s_nop 1
	v_mov_b32_dpp v13, v12 quad_perm:[1,0,3,2] row_mask:0xf bank_mask:0xf bound_ctrl:1
	s_and_saveexec_b64 s[10:11], vcc
	s_cbranch_execz .LBB0_1840
	v_mov_b32_e32 v14, v227
	v_lshlrev_b32_e32 v15, 16, v14
	v_and_b32_e32 v14, 0xffff0000, v14
	v_add_f32_e32 v12, v12, v15
	v_add_f32_e32 v13, v13, v14
	v_cvt_pk_bf16_f32 v12, v12, v13
	ds_write_b32 v2, v12 offset:4096
.LBB0_1840:
	s_or_b64 exec, exec, s[10:11]
	v_mul_f32_e32 v12, v58, v8
	s_nop 1
	v_mov_b32_dpp v13, v12 quad_perm:[1,0,3,2] row_mask:0xf bank_mask:0xf bound_ctrl:1
	s_and_saveexec_b64 s[10:11], vcc
	s_cbranch_execz .LBB0_1842
	v_mov_b32_e32 v14, v228
	v_lshlrev_b32_e32 v15, 16, v14
	v_and_b32_e32 v14, 0xffff0000, v14
	v_add_f32_e32 v12, v12, v15
	v_add_f32_e32 v13, v13, v14
	v_cvt_pk_bf16_f32 v12, v12, v13
	ds_write_b32 v2, v12 offset:4160
.LBB0_1842:
	s_or_b64 exec, exec, s[10:11]
	v_mul_f32_e32 v12, v42, v8
	s_nop 1
	v_mov_b32_dpp v13, v12 quad_perm:[1,0,3,2] row_mask:0xf bank_mask:0xf bound_ctrl:1
	s_and_saveexec_b64 s[10:11], vcc
	s_cbranch_execz .LBB0_1844
	v_mov_b32_e32 v14, v229
	v_lshlrev_b32_e32 v15, 16, v14
	v_and_b32_e32 v14, 0xffff0000, v14
	v_add_f32_e32 v12, v12, v15
	v_add_f32_e32 v13, v13, v14
	v_cvt_pk_bf16_f32 v12, v12, v13
	ds_write_b32 v2, v12 offset:4224
.LBB0_1844:
	s_or_b64 exec, exec, s[10:11]
	v_mul_f32_e32 v8, v26, v8
	s_nop 1
	v_mov_b32_dpp v12, v8 quad_perm:[1,0,3,2] row_mask:0xf bank_mask:0xf bound_ctrl:1
	s_and_saveexec_b64 s[10:11], vcc
	s_cbranch_execz .LBB0_1846
	v_mov_b32_e32 v13, v230
	v_lshlrev_b32_e32 v14, 16, v13
	v_and_b32_e32 v13, 0xffff0000, v13
	v_add_f32_e32 v8, v8, v14
	v_add_f32_e32 v12, v12, v13
	v_cvt_pk_bf16_f32 v8, v8, v12
	ds_write_b32 v2, v8 offset:4288
.LBB0_1846:
	s_or_b64 exec, exec, s[10:11]
	v_mul_f32_e32 v8, v75, v9
	s_nop 1
	v_mov_b32_dpp v12, v8 quad_perm:[1,0,3,2] row_mask:0xf bank_mask:0xf bound_ctrl:1
	s_and_saveexec_b64 s[10:11], vcc
	s_cbranch_execz .LBB0_1848
	v_mov_b32_e32 v13, v231
	v_lshlrev_b32_e32 v14, 16, v13
	v_and_b32_e32 v13, 0xffff0000, v13
	v_add_f32_e32 v8, v8, v14
	v_add_f32_e32 v12, v12, v13
	v_cvt_pk_bf16_f32 v8, v8, v12
	ds_write_b32 v2, v8 offset:4352
.LBB0_1848:
	s_or_b64 exec, exec, s[10:11]
	v_mul_f32_e32 v8, v59, v9
	s_nop 1
	v_mov_b32_dpp v12, v8 quad_perm:[1,0,3,2] row_mask:0xf bank_mask:0xf bound_ctrl:1
	s_and_saveexec_b64 s[10:11], vcc
	s_cbranch_execz .LBB0_1850
	v_mov_b32_e32 v13, v232
	v_lshlrev_b32_e32 v14, 16, v13
	v_and_b32_e32 v13, 0xffff0000, v13
	v_add_f32_e32 v8, v8, v14
	v_add_f32_e32 v12, v12, v13
	v_cvt_pk_bf16_f32 v8, v8, v12
	ds_write_b32 v2, v8 offset:4416
.LBB0_1850:
	s_or_b64 exec, exec, s[10:11]
	v_mul_f32_e32 v8, v43, v9
	s_nop 1
	v_mov_b32_dpp v12, v8 quad_perm:[1,0,3,2] row_mask:0xf bank_mask:0xf bound_ctrl:1
	s_and_saveexec_b64 s[10:11], vcc
	s_cbranch_execz .LBB0_1852
	v_mov_b32_e32 v13, v233
	v_lshlrev_b32_e32 v14, 16, v13
	v_and_b32_e32 v13, 0xffff0000, v13
	v_add_f32_e32 v8, v8, v14
	v_add_f32_e32 v12, v12, v13
	v_cvt_pk_bf16_f32 v8, v8, v12
	ds_write_b32 v2, v8 offset:4480
.LBB0_1852:
	s_or_b64 exec, exec, s[10:11]
	v_mul_f32_e32 v8, v27, v9
	s_nop 1
	v_mov_b32_dpp v9, v8 quad_perm:[1,0,3,2] row_mask:0xf bank_mask:0xf bound_ctrl:1
	s_and_saveexec_b64 s[10:11], vcc
	s_cbranch_execz .LBB0_1854
	v_mov_b32_e32 v12, v234
	v_lshlrev_b32_e32 v13, 16, v12
	v_and_b32_e32 v12, 0xffff0000, v12
	v_add_f32_e32 v8, v8, v13
	v_add_f32_e32 v9, v9, v12
	v_cvt_pk_bf16_f32 v8, v8, v9
	ds_write_b32 v2, v8 offset:4544
.LBB0_1854:
	s_or_b64 exec, exec, s[10:11]
	v_mul_f32_e32 v8, v76, v10
	s_nop 1
	v_mov_b32_dpp v9, v8 quad_perm:[1,0,3,2] row_mask:0xf bank_mask:0xf bound_ctrl:1
	s_and_saveexec_b64 s[10:11], vcc
	s_cbranch_execz .LBB0_1856
	v_mov_b32_e32 v12, v235
	v_lshlrev_b32_e32 v13, 16, v12
	v_and_b32_e32 v12, 0xffff0000, v12
	v_add_f32_e32 v8, v8, v13
	v_add_f32_e32 v9, v9, v12
	v_cvt_pk_bf16_f32 v8, v8, v9
	ds_write_b32 v2, v8 offset:4608
.LBB0_1856:
	s_or_b64 exec, exec, s[10:11]
	v_mul_f32_e32 v8, v60, v10
	s_nop 1
	v_mov_b32_dpp v9, v8 quad_perm:[1,0,3,2] row_mask:0xf bank_mask:0xf bound_ctrl:1
	s_and_saveexec_b64 s[10:11], vcc
	s_cbranch_execz .LBB0_1858
	v_mov_b32_e32 v12, v236
	v_lshlrev_b32_e32 v13, 16, v12
	v_and_b32_e32 v12, 0xffff0000, v12
	v_add_f32_e32 v8, v8, v13
	v_add_f32_e32 v9, v9, v12
	v_cvt_pk_bf16_f32 v8, v8, v9
	ds_write_b32 v2, v8 offset:4672
.LBB0_1858:
	s_or_b64 exec, exec, s[10:11]
	v_mul_f32_e32 v8, v44, v10
	s_nop 1
	v_mov_b32_dpp v9, v8 quad_perm:[1,0,3,2] row_mask:0xf bank_mask:0xf bound_ctrl:1
	s_and_saveexec_b64 s[10:11], vcc
	s_cbranch_execz .LBB0_1860
	v_mov_b32_e32 v12, v237
	v_lshlrev_b32_e32 v13, 16, v12
	v_and_b32_e32 v12, 0xffff0000, v12
	v_add_f32_e32 v8, v8, v13
	v_add_f32_e32 v9, v9, v12
	v_cvt_pk_bf16_f32 v8, v8, v9
	ds_write_b32 v2, v8 offset:4736
.LBB0_1860:
	s_or_b64 exec, exec, s[10:11]
	v_mul_f32_e32 v8, v28, v10
	s_nop 1
	v_mov_b32_dpp v9, v8 quad_perm:[1,0,3,2] row_mask:0xf bank_mask:0xf bound_ctrl:1
	s_and_saveexec_b64 s[10:11], vcc
	s_cbranch_execz .LBB0_1862
	v_mov_b32_e32 v10, v238
	v_lshlrev_b32_e32 v12, 16, v10
	v_and_b32_e32 v10, 0xffff0000, v10
	v_add_f32_e32 v8, v8, v12
	v_add_f32_e32 v9, v9, v10
	v_cvt_pk_bf16_f32 v8, v8, v9
	ds_write_b32 v2, v8 offset:4800
.LBB0_1862:
	s_or_b64 exec, exec, s[10:11]
	v_mul_f32_e32 v8, v77, v11
	s_nop 1
	v_mov_b32_dpp v9, v8 quad_perm:[1,0,3,2] row_mask:0xf bank_mask:0xf bound_ctrl:1
	s_and_saveexec_b64 s[10:11], vcc
	s_cbranch_execz .LBB0_1864
	v_mov_b32_e32 v10, v239
	v_lshlrev_b32_e32 v12, 16, v10
	v_and_b32_e32 v10, 0xffff0000, v10
	v_add_f32_e32 v8, v8, v12
	v_add_f32_e32 v9, v9, v10
	v_cvt_pk_bf16_f32 v8, v8, v9
	ds_write_b32 v2, v8 offset:4864
.LBB0_1864:
	s_or_b64 exec, exec, s[10:11]
	v_mul_f32_e32 v8, v61, v11
	s_nop 1
	v_mov_b32_dpp v9, v8 quad_perm:[1,0,3,2] row_mask:0xf bank_mask:0xf bound_ctrl:1
	s_and_saveexec_b64 s[10:11], vcc
	s_cbranch_execz .LBB0_1866
	v_mov_b32_e32 v10, v92
	v_lshlrev_b32_e32 v12, 16, v10
	v_and_b32_e32 v10, 0xffff0000, v10
	v_add_f32_e32 v8, v8, v12
	v_add_f32_e32 v9, v9, v10
	v_cvt_pk_bf16_f32 v8, v8, v9
	ds_write_b32 v2, v8 offset:4928
.LBB0_1866:
	s_or_b64 exec, exec, s[10:11]
	v_mul_f32_e32 v8, v45, v11
	s_nop 1
	v_mov_b32_dpp v9, v8 quad_perm:[1,0,3,2] row_mask:0xf bank_mask:0xf bound_ctrl:1
	s_and_saveexec_b64 s[10:11], vcc
	s_cbranch_execz .LBB0_1868
	v_mov_b32_e32 v10, v93
	v_lshlrev_b32_e32 v12, 16, v10
	v_and_b32_e32 v10, 0xffff0000, v10
	v_add_f32_e32 v8, v8, v12
	v_add_f32_e32 v9, v9, v10
	v_cvt_pk_bf16_f32 v8, v8, v9
	ds_write_b32 v2, v8 offset:4992
.LBB0_1868:
	s_or_b64 exec, exec, s[10:11]
	v_mul_f32_e32 v8, v29, v11
	s_nop 1
	v_mov_b32_dpp v9, v8 quad_perm:[1,0,3,2] row_mask:0xf bank_mask:0xf bound_ctrl:1
	s_and_saveexec_b64 s[10:11], vcc
	s_cbranch_execz .LBB0_1870
	v_mov_b32_e32 v10, v94
	v_lshlrev_b32_e32 v11, 16, v10
	v_and_b32_e32 v10, 0xffff0000, v10
	v_add_f32_e32 v8, v8, v11
	v_add_f32_e32 v9, v9, v10
	v_cvt_pk_bf16_f32 v8, v8, v9
	ds_write_b32 v2, v8 offset:5056
.LBB0_1870:
	s_or_b64 exec, exec, s[10:11]
	s_waitcnt lgkmcnt(0)
	v_mul_f32_e32 v8, v78, v4
	s_nop 1
	v_mov_b32_dpp v9, v8 quad_perm:[1,0,3,2] row_mask:0xf bank_mask:0xf bound_ctrl:1
	s_and_saveexec_b64 s[10:11], vcc
	s_cbranch_execz .LBB0_1872
	v_mov_b32_e32 v10, v95
	v_lshlrev_b32_e32 v11, 16, v10
	v_and_b32_e32 v10, 0xffff0000, v10
	v_add_f32_e32 v8, v8, v11
	v_add_f32_e32 v9, v9, v10
	v_cvt_pk_bf16_f32 v8, v8, v9
	ds_write_b32 v2, v8 offset:6144
.LBB0_1872:
	s_or_b64 exec, exec, s[10:11]
	v_mul_f32_e32 v8, v62, v4
	s_nop 1
	v_mov_b32_dpp v9, v8 quad_perm:[1,0,3,2] row_mask:0xf bank_mask:0xf bound_ctrl:1
	s_and_saveexec_b64 s[10:11], vcc
	s_cbranch_execz .LBB0_1874
	v_mov_b32_e32 v10, v96
	v_lshlrev_b32_e32 v11, 16, v10
	v_and_b32_e32 v10, 0xffff0000, v10
	v_add_f32_e32 v8, v8, v11
	v_add_f32_e32 v9, v9, v10
	v_cvt_pk_bf16_f32 v8, v8, v9
	ds_write_b32 v2, v8 offset:6208
.LBB0_1874:
	s_or_b64 exec, exec, s[10:11]
	v_mul_f32_e32 v8, v46, v4
	s_nop 1
	v_mov_b32_dpp v9, v8 quad_perm:[1,0,3,2] row_mask:0xf bank_mask:0xf bound_ctrl:1
	s_and_saveexec_b64 s[10:11], vcc
	s_cbranch_execz .LBB0_1876
	v_mov_b32_e32 v10, v97
	v_lshlrev_b32_e32 v11, 16, v10
	v_and_b32_e32 v10, 0xffff0000, v10
	v_add_f32_e32 v8, v8, v11
	v_add_f32_e32 v9, v9, v10
	v_cvt_pk_bf16_f32 v8, v8, v9
	ds_write_b32 v2, v8 offset:6272
.LBB0_1876:
	s_or_b64 exec, exec, s[10:11]
	v_mul_f32_e32 v4, v30, v4
	s_nop 1
	v_mov_b32_dpp v8, v4 quad_perm:[1,0,3,2] row_mask:0xf bank_mask:0xf bound_ctrl:1
	s_and_saveexec_b64 s[10:11], vcc
	s_cbranch_execz .LBB0_1878
	v_mov_b32_e32 v9, v98
	v_lshlrev_b32_e32 v10, 16, v9
	v_and_b32_e32 v9, 0xffff0000, v9
	v_add_f32_e32 v4, v4, v10
	v_add_f32_e32 v8, v8, v9
	v_cvt_pk_bf16_f32 v4, v4, v8
	ds_write_b32 v2, v4 offset:6336
.LBB0_1878:
	s_or_b64 exec, exec, s[10:11]
	v_mul_f32_e32 v4, v79, v5
	s_nop 1
	v_mov_b32_dpp v8, v4 quad_perm:[1,0,3,2] row_mask:0xf bank_mask:0xf bound_ctrl:1
	s_and_saveexec_b64 s[10:11], vcc
	s_cbranch_execz .LBB0_1880
	v_mov_b32_e32 v9, v99
	v_lshlrev_b32_e32 v10, 16, v9
	v_and_b32_e32 v9, 0xffff0000, v9
	v_add_f32_e32 v4, v4, v10
	v_add_f32_e32 v8, v8, v9
	v_cvt_pk_bf16_f32 v4, v4, v8
	ds_write_b32 v2, v4 offset:6400
.LBB0_1880:
	s_or_b64 exec, exec, s[10:11]
	v_mul_f32_e32 v4, v63, v5
	s_nop 1
	v_mov_b32_dpp v8, v4 quad_perm:[1,0,3,2] row_mask:0xf bank_mask:0xf bound_ctrl:1
	s_and_saveexec_b64 s[10:11], vcc
	s_cbranch_execz .LBB0_1882
	v_mov_b32_e32 v9, v100
	v_lshlrev_b32_e32 v10, 16, v9
	v_and_b32_e32 v9, 0xffff0000, v9
	v_add_f32_e32 v4, v4, v10
	v_add_f32_e32 v8, v8, v9
	v_cvt_pk_bf16_f32 v4, v4, v8
	ds_write_b32 v2, v4 offset:6464
.LBB0_1882:
	s_or_b64 exec, exec, s[10:11]
	v_mul_f32_e32 v4, v47, v5
	s_nop 1
	v_mov_b32_dpp v8, v4 quad_perm:[1,0,3,2] row_mask:0xf bank_mask:0xf bound_ctrl:1
	s_and_saveexec_b64 s[10:11], vcc
	s_cbranch_execz .LBB0_1884
	v_mov_b32_e32 v9, v101
	v_lshlrev_b32_e32 v10, 16, v9
	v_and_b32_e32 v9, 0xffff0000, v9
	v_add_f32_e32 v4, v4, v10
	v_add_f32_e32 v8, v8, v9
	v_cvt_pk_bf16_f32 v4, v4, v8
	ds_write_b32 v2, v4 offset:6528
.LBB0_1884:
	s_or_b64 exec, exec, s[10:11]
	v_mul_f32_e32 v4, v31, v5
	s_nop 1
	v_mov_b32_dpp v5, v4 quad_perm:[1,0,3,2] row_mask:0xf bank_mask:0xf bound_ctrl:1
	s_and_saveexec_b64 s[10:11], vcc
	s_cbranch_execz .LBB0_1886
	v_mov_b32_e32 v8, v102
	v_lshlrev_b32_e32 v9, 16, v8
	v_and_b32_e32 v8, 0xffff0000, v8
	v_add_f32_e32 v4, v4, v9
	v_add_f32_e32 v5, v5, v8
	v_cvt_pk_bf16_f32 v4, v4, v5
	ds_write_b32 v2, v4 offset:6592
.LBB0_1886:
	s_or_b64 exec, exec, s[10:11]
	v_mul_f32_e32 v4, v80, v6
	s_nop 1
	v_mov_b32_dpp v5, v4 quad_perm:[1,0,3,2] row_mask:0xf bank_mask:0xf bound_ctrl:1
	s_and_saveexec_b64 s[10:11], vcc
	s_cbranch_execz .LBB0_1888
	v_mov_b32_e32 v8, v103
	v_lshlrev_b32_e32 v9, 16, v8
	v_and_b32_e32 v8, 0xffff0000, v8
	v_add_f32_e32 v4, v4, v9
	v_add_f32_e32 v5, v5, v8
	v_cvt_pk_bf16_f32 v4, v4, v5
	ds_write_b32 v2, v4 offset:6656
.LBB0_1888:
	s_or_b64 exec, exec, s[10:11]
	v_mul_f32_e32 v4, v64, v6
	s_nop 1
	v_mov_b32_dpp v5, v4 quad_perm:[1,0,3,2] row_mask:0xf bank_mask:0xf bound_ctrl:1
	s_and_saveexec_b64 s[10:11], vcc
	s_cbranch_execz .LBB0_1890
	v_mov_b32_e32 v8, v104
	v_lshlrev_b32_e32 v9, 16, v8
	v_and_b32_e32 v8, 0xffff0000, v8
	v_add_f32_e32 v4, v4, v9
	v_add_f32_e32 v5, v5, v8
	v_cvt_pk_bf16_f32 v4, v4, v5
	ds_write_b32 v2, v4 offset:6720
.LBB0_1890:
	s_or_b64 exec, exec, s[10:11]
	v_mul_f32_e32 v4, v48, v6
	s_nop 1
	v_mov_b32_dpp v5, v4 quad_perm:[1,0,3,2] row_mask:0xf bank_mask:0xf bound_ctrl:1
	s_and_saveexec_b64 s[10:11], vcc
	s_cbranch_execz .LBB0_1892
	v_mov_b32_e32 v8, v105
	v_lshlrev_b32_e32 v9, 16, v8
	v_and_b32_e32 v8, 0xffff0000, v8
	v_add_f32_e32 v4, v4, v9
	v_add_f32_e32 v5, v5, v8
	v_cvt_pk_bf16_f32 v4, v4, v5
	ds_write_b32 v2, v4 offset:6784
.LBB0_1892:
	s_or_b64 exec, exec, s[10:11]
	v_mul_f32_e32 v4, v32, v6
	s_nop 1
	v_mov_b32_dpp v5, v4 quad_perm:[1,0,3,2] row_mask:0xf bank_mask:0xf bound_ctrl:1
	s_and_saveexec_b64 s[10:11], vcc
	s_cbranch_execz .LBB0_1894
	v_mov_b32_e32 v6, v106
	v_lshlrev_b32_e32 v8, 16, v6
	v_and_b32_e32 v6, 0xffff0000, v6
	v_add_f32_e32 v4, v4, v8
	v_add_f32_e32 v5, v5, v6
	v_cvt_pk_bf16_f32 v4, v4, v5
	ds_write_b32 v2, v4 offset:6848
.LBB0_1894:
	s_or_b64 exec, exec, s[10:11]
	v_mul_f32_e32 v4, v81, v7
	s_nop 1
	v_mov_b32_dpp v5, v4 quad_perm:[1,0,3,2] row_mask:0xf bank_mask:0xf bound_ctrl:1
	s_and_saveexec_b64 s[10:11], vcc
	s_cbranch_execz .LBB0_1896
	v_mov_b32_e32 v6, v107
	v_lshlrev_b32_e32 v8, 16, v6
	v_and_b32_e32 v6, 0xffff0000, v6
	v_add_f32_e32 v4, v4, v8
	v_add_f32_e32 v5, v5, v6
	v_cvt_pk_bf16_f32 v4, v4, v5
	ds_write_b32 v2, v4 offset:6912
.LBB0_1896:
	s_or_b64 exec, exec, s[10:11]
	v_mul_f32_e32 v4, v65, v7
	s_nop 1
	v_mov_b32_dpp v5, v4 quad_perm:[1,0,3,2] row_mask:0xf bank_mask:0xf bound_ctrl:1
	s_and_saveexec_b64 s[10:11], vcc
	s_cbranch_execz .LBB0_1898
	v_mov_b32_e32 v6, v108
	v_lshlrev_b32_e32 v8, 16, v6
	v_and_b32_e32 v6, 0xffff0000, v6
	v_add_f32_e32 v4, v4, v8
	v_add_f32_e32 v5, v5, v6
	v_cvt_pk_bf16_f32 v4, v4, v5
	ds_write_b32 v2, v4 offset:6976
.LBB0_1898:
	s_or_b64 exec, exec, s[10:11]
	v_mul_f32_e32 v4, v49, v7
	s_nop 1
	v_mov_b32_dpp v5, v4 quad_perm:[1,0,3,2] row_mask:0xf bank_mask:0xf bound_ctrl:1
	s_and_saveexec_b64 s[10:11], vcc
	s_cbranch_execz .LBB0_1900
	v_mov_b32_e32 v6, v109
	v_lshlrev_b32_e32 v8, 16, v6
	v_and_b32_e32 v6, 0xffff0000, v6
	v_add_f32_e32 v4, v4, v8
	v_add_f32_e32 v5, v5, v6
	v_cvt_pk_bf16_f32 v4, v4, v5
	ds_write_b32 v2, v4 offset:7040
.LBB0_1900:
	s_or_b64 exec, exec, s[10:11]
	v_mul_f32_e32 v4, v33, v7
	s_nop 1
	v_mov_b32_dpp v5, v4 quad_perm:[1,0,3,2] row_mask:0xf bank_mask:0xf bound_ctrl:1
	s_and_saveexec_b64 s[10:11], vcc
	s_cbranch_execz .LBB0_1902
	v_mov_b32_e32 v6, v110
	v_lshlrev_b32_e32 v7, 16, v6
	v_and_b32_e32 v6, 0xffff0000, v6
	v_add_f32_e32 v4, v4, v7
	v_add_f32_e32 v5, v5, v6
	v_cvt_pk_bf16_f32 v4, v4, v5
	ds_write_b32 v2, v4 offset:7104

.LBB0_1938:
	s_or_b64 exec, exec, s[8:9]
	v_ashrrev_i32_e32 v16, 5, v194
	s_waitcnt lgkmcnt(0)
	s_waitcnt vmcnt(1)
	v_lshl_add_u32 v2, v16, 4, s33
	v_readlane_b32 s2, v250, 37
	s_load_dwordx4 s[8:11], s[0:1], 0xd0
	ds_read_b128 v[82:85], v2
	ds_read_b128 v[12:15], v2 offset:32
	ds_read_b128 v[8:11], v2 offset:64
	s_waitcnt vmcnt(0)
	ds_read_b128 v[4:7], v2 offset:96
	v_lshlrev_b32_e32 v2, 1, v194
	s_or_b32 s2, s79, s2
	v_lshlrev_b32_e32 v17, 10, v16
	v_and_b32_e32 v2, 60, v2
	v_lshl_add_u32 v16, v16, 2, s2
	v_add3_u32 v86, s83, v17, v2
	v_ashrrev_i32_e32 v17, 31, v16
	v_lshlrev_b64 v[16:17], 13, v[16:17]
	s_waitcnt lgkmcnt(0)
	v_lshl_add_u64 v[16:17], s[8:9], 0, v[16:17]
	s_lshl_b32 s84, s15, 1
	v_lshl_add_u64 v[16:17], v[16:17], 0, s[84:85]
	s_waitcnt lgkmcnt(0)
	v_lshl_add_u64 v[16:17], v[16:17], 0, v[2:3]
	v_and_b32_e32 v2, 1, v194
	v_cmp_eq_u32_e64 s[8:9], 0, v2
	ds_read_b32 v195, v86
	ds_read_b32 v196, v86 offset:64
	ds_read_b32 v197, v86 offset:128
	ds_read_b32 v198, v86 offset:192
	ds_read_b32 v199, v86 offset:256
	ds_read_b32 v200, v86 offset:320
	ds_read_b32 v201, v86 offset:384
	ds_read_b32 v202, v86 offset:448
	ds_read_b32 v203, v86 offset:512
	ds_read_b32 v204, v86 offset:576
	ds_read_b32 v205, v86 offset:640
	ds_read_b32 v206, v86 offset:704
	ds_read_b32 v207, v86 offset:768
	ds_read_b32 v208, v86 offset:832
	ds_read_b32 v209, v86 offset:896
	ds_read_b32 v210, v86 offset:960
	ds_read_b32 v211, v86 offset:2048
	ds_read_b32 v212, v86 offset:2112
	ds_read_b32 v213, v86 offset:2176
	ds_read_b32 v214, v86 offset:2240
	ds_read_b32 v215, v86 offset:2304
	ds_read_b32 v216, v86 offset:2368
	ds_read_b32 v217, v86 offset:2432
	ds_read_b32 v218, v86 offset:2496
	ds_read_b32 v219, v86 offset:2560
	ds_read_b32 v220, v86 offset:2624
	ds_read_b32 v221, v86 offset:2688
	ds_read_b32 v222, v86 offset:2752
	ds_read_b32 v223, v86 offset:2816
	ds_read_b32 v224, v86 offset:2880
	ds_read_b32 v225, v86 offset:2944
	ds_read_b32 v226, v86 offset:3008
	ds_read_b32 v227, v86 offset:4096
	ds_read_b32 v228, v86 offset:4160
	ds_read_b32 v229, v86 offset:4224
	ds_read_b32 v230, v86 offset:4288
	ds_read_b32 v231, v86 offset:4352
	ds_read_b32 v232, v86 offset:4416
	ds_read_b32 v233, v86 offset:4480
	ds_read_b32 v234, v86 offset:4544
	ds_read_b32 v235, v86 offset:4608
	ds_read_b32 v236, v86 offset:4672
	ds_read_b32 v237, v86 offset:4736
	ds_read_b32 v238, v86 offset:4800
	ds_read_b32 v239, v86 offset:4864
	ds_read_b32 v92, v86 offset:4928
	ds_read_b32 v93, v86 offset:4992
	ds_read_b32 v94, v86 offset:5056
	ds_read_b32 v95, v86 offset:6144
	ds_read_b32 v96, v86 offset:6208
	ds_read_b32 v97, v86 offset:6272
	ds_read_b32 v98, v86 offset:6336
	ds_read_b32 v99, v86 offset:6400
	ds_read_b32 v100, v86 offset:6464
	ds_read_b32 v101, v86 offset:6528
	ds_read_b32 v102, v86 offset:6592
	ds_read_b32 v103, v86 offset:6656
	ds_read_b32 v104, v86 offset:6720
	ds_read_b32 v105, v86 offset:6784
	ds_read_b32 v106, v86 offset:6848
	ds_read_b32 v107, v86 offset:6912
	ds_read_b32 v108, v86 offset:6976
	ds_read_b32 v109, v86 offset:7040
	ds_read_b32 v110, v86 offset:7104
	s_waitcnt lgkmcnt(0)
	v_mul_f32_e32 v2, v66, v82
	s_nop 1
	v_mov_b32_dpp v66, v2 quad_perm:[1,0,3,2] row_mask:0xf bank_mask:0xf bound_ctrl:1
	s_and_saveexec_b64 s[10:11], s[8:9]
	s_cbranch_execz .LBB0_1940
	v_mov_b32_e32 v87, v195
	v_lshlrev_b32_e32 v88, 16, v87
	v_and_b32_e32 v87, 0xffff0000, v87
	v_add_f32_e32 v2, v2, v88
	v_add_f32_e32 v66, v66, v87
	v_cvt_pk_bf16_f32 v2, v2, v66
	global_store_dword v[16:17], v2, off
.LBB0_1940:
	s_or_b64 exec, exec, s[10:11]
	v_mul_f32_e32 v2, v50, v82
	s_nop 1
	v_mov_b32_dpp v50, v2 quad_perm:[1,0,3,2] row_mask:0xf bank_mask:0xf bound_ctrl:1
	s_and_saveexec_b64 s[10:11], s[8:9]
	s_cbranch_execz .LBB0_1942
	v_mov_b32_e32 v66, v196
	v_lshlrev_b32_e32 v87, 16, v66
	v_and_b32_e32 v66, 0xffff0000, v66
	v_add_f32_e32 v2, v2, v87
	v_add_f32_e32 v50, v50, v66
	v_cvt_pk_bf16_f32 v2, v2, v50
	global_store_dword v[16:17], v2, off offset:64
.LBB0_1942:
	s_or_b64 exec, exec, s[10:11]
	v_mul_f32_e32 v2, v34, v82
	s_nop 1
	v_mov_b32_dpp v34, v2 quad_perm:[1,0,3,2] row_mask:0xf bank_mask:0xf bound_ctrl:1
	s_and_saveexec_b64 s[10:11], s[8:9]
	s_cbranch_execz .LBB0_1944
	v_mov_b32_e32 v50, v197
	v_lshlrev_b32_e32 v66, 16, v50
	v_and_b32_e32 v50, 0xffff0000, v50
	v_add_f32_e32 v2, v2, v66
	v_add_f32_e32 v34, v34, v50
	v_cvt_pk_bf16_f32 v2, v2, v34
	global_store_dword v[16:17], v2, off offset:128
.LBB0_1944:
	s_or_b64 exec, exec, s[10:11]
	v_mul_f32_e32 v2, v18, v82
	s_nop 1
	v_mov_b32_dpp v18, v2 quad_perm:[1,0,3,2] row_mask:0xf bank_mask:0xf bound_ctrl:1
	s_and_saveexec_b64 s[10:11], s[8:9]
	s_cbranch_execz .LBB0_1946
	v_mov_b32_e32 v34, v198
	v_lshlrev_b32_e32 v50, 16, v34
	v_and_b32_e32 v34, 0xffff0000, v34
	v_add_f32_e32 v2, v2, v50
	v_add_f32_e32 v18, v18, v34
	v_cvt_pk_bf16_f32 v2, v2, v18
	global_store_dword v[16:17], v2, off offset:192
.LBB0_1946:
	s_or_b64 exec, exec, s[10:11]
	v_mul_f32_e32 v2, v67, v83
	s_nop 1
	v_mov_b32_dpp v18, v2 quad_perm:[1,0,3,2] row_mask:0xf bank_mask:0xf bound_ctrl:1
	s_and_saveexec_b64 s[10:11], s[8:9]
	s_cbranch_execz .LBB0_1948
	v_mov_b32_e32 v34, v199
	v_add_co_u32_e32 v66, vcc, 0x2000, v16
	v_lshlrev_b32_e32 v50, 16, v34
	v_and_b32_e32 v34, 0xffff0000, v34
	v_add_f32_e32 v2, v2, v50
	v_addc_co_u32_e32 v67, vcc, 0, v17, vcc
	v_add_f32_e32 v18, v18, v34
	v_cvt_pk_bf16_f32 v2, v2, v18
	global_store_dword v[66:67], v2, off
.LBB0_1948:
	s_or_b64 exec, exec, s[10:11]
	v_mul_f32_e32 v2, v51, v83
	s_nop 1
	v_mov_b32_dpp v18, v2 quad_perm:[1,0,3,2] row_mask:0xf bank_mask:0xf bound_ctrl:1
	s_and_saveexec_b64 s[10:11], s[8:9]
	s_cbranch_execz .LBB0_1950
	v_mov_b32_e32 v34, v200
	v_add_co_u32_e32 v50, vcc, 0x2000, v16
	v_lshlrev_b32_e32 v51, 16, v34
	v_and_b32_e32 v34, 0xffff0000, v34
	v_add_f32_e32 v2, v2, v51
	v_addc_co_u32_e32 v51, vcc, 0, v17, vcc
	v_add_f32_e32 v18, v18, v34
	v_cvt_pk_bf16_f32 v2, v2, v18
	global_store_dword v[50:51], v2, off offset:64
.LBB0_1950:
	s_or_b64 exec, exec, s[10:11]
	v_mul_f32_e32 v2, v35, v83
	s_nop 1
	v_mov_b32_dpp v18, v2 quad_perm:[1,0,3,2] row_mask:0xf bank_mask:0xf bound_ctrl:1
	s_and_saveexec_b64 s[10:11], s[8:9]
	s_cbranch_execz .LBB0_1952
	v_mov_b32_e32 v35, v201
	v_add_co_u32_e32 v34, vcc, 0x2000, v16
	v_lshlrev_b32_e32 v50, 16, v35
	v_and_b32_e32 v35, 0xffff0000, v35
	v_add_f32_e32 v2, v2, v50
	v_add_f32_e32 v18, v18, v35
	v_addc_co_u32_e32 v35, vcc, 0, v17, vcc
	v_cvt_pk_bf16_f32 v2, v2, v18
	global_store_dword v[34:35], v2, off offset:128
.LBB0_1952:
	s_or_b64 exec, exec, s[10:11]
	v_mul_f32_e32 v2, v19, v83
	s_nop 1
	v_mov_b32_dpp v18, v2 quad_perm:[1,0,3,2] row_mask:0xf bank_mask:0xf bound_ctrl:1
	s_and_saveexec_b64 s[10:11], s[8:9]
	s_cbranch_execz .LBB0_1954
	v_mov_b32_e32 v19, v202
	v_add_co_u32_e32 v34, vcc, 0x2000, v16
	v_lshlrev_b32_e32 v35, 16, v19
	v_and_b32_e32 v19, 0xffff0000, v19
	v_add_f32_e32 v2, v2, v35
	v_addc_co_u32_e32 v35, vcc, 0, v17, vcc
	v_add_f32_e32 v18, v18, v19
	v_cvt_pk_bf16_f32 v2, v2, v18
	global_store_dword v[34:35], v2, off offset:192
.LBB0_1954:
	s_or_b64 exec, exec, s[10:11]
	v_mul_f32_e32 v2, v68, v84
	s_nop 1
	v_mov_b32_dpp v18, v2 quad_perm:[1,0,3,2] row_mask:0xf bank_mask:0xf bound_ctrl:1
	s_and_saveexec_b64 s[10:11], s[8:9]
	s_cbranch_execz .LBB0_1956
	v_mov_b32_e32 v19, v203
	v_add_co_u32_e32 v34, vcc, 0x4000, v16
	v_lshlrev_b32_e32 v35, 16, v19
	v_and_b32_e32 v19, 0xffff0000, v19
	v_add_f32_e32 v2, v2, v35
	v_addc_co_u32_e32 v35, vcc, 0, v17, vcc
	v_add_f32_e32 v18, v18, v19
	v_cvt_pk_bf16_f32 v2, v2, v18
	global_store_dword v[34:35], v2, off
.LBB0_1956:
	s_or_b64 exec, exec, s[10:11]
	v_mul_f32_e32 v2, v52, v84
	s_nop 1
	v_mov_b32_dpp v18, v2 quad_perm:[1,0,3,2] row_mask:0xf bank_mask:0xf bound_ctrl:1
	s_and_saveexec_b64 s[10:11], s[8:9]
	s_cbranch_execz .LBB0_1958
	v_mov_b32_e32 v19, v204
	v_add_co_u32_e32 v34, vcc, 0x4000, v16
	v_lshlrev_b32_e32 v35, 16, v19
	v_and_b32_e32 v19, 0xffff0000, v19
	v_add_f32_e32 v2, v2, v35
	v_addc_co_u32_e32 v35, vcc, 0, v17, vcc
	v_add_f32_e32 v18, v18, v19
	v_cvt_pk_bf16_f32 v2, v2, v18
	global_store_dword v[34:35], v2, off offset:64
.LBB0_1958:
	s_or_b64 exec, exec, s[10:11]
	v_mul_f32_e32 v2, v36, v84
	s_nop 1
	v_mov_b32_dpp v18, v2 quad_perm:[1,0,3,2] row_mask:0xf bank_mask:0xf bound_ctrl:1
	s_and_saveexec_b64 s[10:11], s[8:9]
	s_cbranch_execz .LBB0_1960
	v_mov_b32_e32 v19, v205
	v_add_co_u32_e32 v34, vcc, 0x4000, v16
	v_lshlrev_b32_e32 v35, 16, v19
	v_and_b32_e32 v19, 0xffff0000, v19
	v_add_f32_e32 v2, v2, v35
	v_addc_co_u32_e32 v35, vcc, 0, v17, vcc
	v_add_f32_e32 v18, v18, v19
	v_cvt_pk_bf16_f32 v2, v2, v18
	global_store_dword v[34:35], v2, off offset:128
.LBB0_1960:
	s_or_b64 exec, exec, s[10:11]
	v_mul_f32_e32 v2, v20, v84
	s_nop 1
	v_mov_b32_dpp v18, v2 quad_perm:[1,0,3,2] row_mask:0xf bank_mask:0xf bound_ctrl:1
	s_and_saveexec_b64 s[10:11], s[8:9]
	s_cbranch_execz .LBB0_1962
	v_mov_b32_e32 v19, v206
	v_add_co_u32_e32 v34, vcc, 0x4000, v16
	v_lshlrev_b32_e32 v20, 16, v19
	v_and_b32_e32 v19, 0xffff0000, v19
	v_add_f32_e32 v2, v2, v20
	v_addc_co_u32_e32 v35, vcc, 0, v17, vcc
	v_add_f32_e32 v18, v18, v19
	v_cvt_pk_bf16_f32 v2, v2, v18
	global_store_dword v[34:35], v2, off offset:192
.LBB0_1962:
	s_or_b64 exec, exec, s[10:11]
	v_mul_f32_e32 v2, v69, v85
	s_nop 1
	v_mov_b32_dpp v18, v2 quad_perm:[1,0,3,2] row_mask:0xf bank_mask:0xf bound_ctrl:1
	s_and_saveexec_b64 s[10:11], s[8:9]
	s_cbranch_execz .LBB0_1964
	v_mov_b32_e32 v19, v207
	v_add_co_u32_e32 v34, vcc, 0x6000, v16
	v_lshlrev_b32_e32 v20, 16, v19
	v_and_b32_e32 v19, 0xffff0000, v19
	v_add_f32_e32 v2, v2, v20
	v_addc_co_u32_e32 v35, vcc, 0, v17, vcc
	v_add_f32_e32 v18, v18, v19
	v_cvt_pk_bf16_f32 v2, v2, v18
	global_store_dword v[34:35], v2, off
.LBB0_1964:
	s_or_b64 exec, exec, s[10:11]
	v_mul_f32_e32 v2, v53, v85
	s_nop 1
	v_mov_b32_dpp v18, v2 quad_perm:[1,0,3,2] row_mask:0xf bank_mask:0xf bound_ctrl:1
	s_and_saveexec_b64 s[10:11], s[8:9]
	s_cbranch_execz .LBB0_1966
	v_mov_b32_e32 v19, v208
	v_add_co_u32_e32 v34, vcc, 0x6000, v16
	v_lshlrev_b32_e32 v20, 16, v19
	v_and_b32_e32 v19, 0xffff0000, v19
	v_add_f32_e32 v2, v2, v20
	v_addc_co_u32_e32 v35, vcc, 0, v17, vcc
	v_add_f32_e32 v18, v18, v19
	v_cvt_pk_bf16_f32 v2, v2, v18
	global_store_dword v[34:35], v2, off offset:64
.LBB0_1966:
	s_or_b64 exec, exec, s[10:11]
	v_mul_f32_e32 v2, v37, v85
	s_nop 1
	v_mov_b32_dpp v18, v2 quad_perm:[1,0,3,2] row_mask:0xf bank_mask:0xf bound_ctrl:1
	s_and_saveexec_b64 s[10:11], s[8:9]
	s_cbranch_execz .LBB0_1968
	v_mov_b32_e32 v19, v209
	v_add_co_u32_e32 v34, vcc, 0x6000, v16
	v_lshlrev_b32_e32 v20, 16, v19
	v_and_b32_e32 v19, 0xffff0000, v19
	v_add_f32_e32 v2, v2, v20
	v_addc_co_u32_e32 v35, vcc, 0, v17, vcc
	v_add_f32_e32 v18, v18, v19
	v_cvt_pk_bf16_f32 v2, v2, v18
	global_store_dword v[34:35], v2, off offset:128
.LBB0_1968:
	s_or_b64 exec, exec, s[10:11]
	v_mul_f32_e32 v2, v21, v85
	s_nop 1
	v_mov_b32_dpp v18, v2 quad_perm:[1,0,3,2] row_mask:0xf bank_mask:0xf bound_ctrl:1
	s_and_saveexec_b64 s[10:11], s[8:9]
	s_cbranch_execz .LBB0_1970
	v_mov_b32_e32 v19, v210
	v_add_co_u32_e32 v20, vcc, 0x6000, v16
	v_lshlrev_b32_e32 v21, 16, v19
	v_and_b32_e32 v19, 0xffff0000, v19
	v_add_f32_e32 v2, v2, v21
	v_addc_co_u32_e32 v21, vcc, 0, v17, vcc
	v_add_f32_e32 v18, v18, v19
	v_cvt_pk_bf16_f32 v2, v2, v18
	global_store_dword v[20:21], v2, off offset:192
.LBB0_1970:
	s_or_b64 exec, exec, s[10:11]
	v_mul_f32_e32 v2, v70, v12
	s_nop 1
	v_mov_b32_dpp v18, v2 quad_perm:[1,0,3,2] row_mask:0xf bank_mask:0xf bound_ctrl:1
	s_and_saveexec_b64 s[10:11], s[8:9]
	s_cbranch_execz .LBB0_1972
	v_mov_b32_e32 v19, v211
	v_add_co_u32_e32 v20, vcc, 0x10000, v16
	v_lshlrev_b32_e32 v21, 16, v19
	v_and_b32_e32 v19, 0xffff0000, v19
	v_add_f32_e32 v2, v2, v21
	v_addc_co_u32_e32 v21, vcc, 0, v17, vcc
	v_add_f32_e32 v18, v18, v19
	v_cvt_pk_bf16_f32 v2, v2, v18
	global_store_dword v[20:21], v2, off
.LBB0_1972:
	s_or_b64 exec, exec, s[10:11]
	v_mul_f32_e32 v2, v54, v12
	s_nop 1
	v_mov_b32_dpp v18, v2 quad_perm:[1,0,3,2] row_mask:0xf bank_mask:0xf bound_ctrl:1
	s_and_saveexec_b64 s[10:11], s[8:9]
	s_cbranch_execz .LBB0_1974
	v_mov_b32_e32 v19, v212
	v_add_co_u32_e32 v20, vcc, 0x10000, v16
	v_lshlrev_b32_e32 v21, 16, v19
	v_and_b32_e32 v19, 0xffff0000, v19
	v_add_f32_e32 v2, v2, v21
	v_addc_co_u32_e32 v21, vcc, 0, v17, vcc
	v_add_f32_e32 v18, v18, v19
	v_cvt_pk_bf16_f32 v2, v2, v18
	global_store_dword v[20:21], v2, off offset:64
.LBB0_1974:
	s_or_b64 exec, exec, s[10:11]
	v_mul_f32_e32 v2, v38, v12
	s_nop 1
	v_mov_b32_dpp v18, v2 quad_perm:[1,0,3,2] row_mask:0xf bank_mask:0xf bound_ctrl:1
	s_and_saveexec_b64 s[10:11], s[8:9]
	s_cbranch_execz .LBB0_1976
	v_mov_b32_e32 v19, v213
	v_add_co_u32_e32 v20, vcc, 0x10000, v16
	v_lshlrev_b32_e32 v21, 16, v19
	v_and_b32_e32 v19, 0xffff0000, v19
	v_add_f32_e32 v2, v2, v21
	v_addc_co_u32_e32 v21, vcc, 0, v17, vcc
	v_add_f32_e32 v18, v18, v19
	v_cvt_pk_bf16_f32 v2, v2, v18
	global_store_dword v[20:21], v2, off offset:128
.LBB0_1976:
	s_or_b64 exec, exec, s[10:11]
	v_mul_f32_e32 v2, v22, v12
	s_nop 1
	v_mov_b32_dpp v12, v2 quad_perm:[1,0,3,2] row_mask:0xf bank_mask:0xf bound_ctrl:1
	s_and_saveexec_b64 s[10:11], s[8:9]
	s_cbranch_execz .LBB0_1978
	v_mov_b32_e32 v19, v214
	v_add_co_u32_e32 v18, vcc, 0x10000, v16
	v_lshlrev_b32_e32 v20, 16, v19
	v_and_b32_e32 v19, 0xffff0000, v19
	v_add_f32_e32 v2, v2, v20
	v_add_f32_e32 v12, v12, v19
	v_addc_co_u32_e32 v19, vcc, 0, v17, vcc
	v_cvt_pk_bf16_f32 v2, v2, v12
	global_store_dword v[18:19], v2, off offset:192
.LBB0_1978:
	s_or_b64 exec, exec, s[10:11]
	v_mul_f32_e32 v2, v71, v13
	s_nop 1
	v_mov_b32_dpp v12, v2 quad_perm:[1,0,3,2] row_mask:0xf bank_mask:0xf bound_ctrl:1
	s_and_saveexec_b64 s[10:11], s[8:9]
	s_cbranch_execz .LBB0_1980
	v_mov_b32_e32 v19, v215
	v_add_co_u32_e32 v18, vcc, 0x12000, v16
	v_lshlrev_b32_e32 v20, 16, v19
	v_and_b32_e32 v19, 0xffff0000, v19
	v_add_f32_e32 v2, v2, v20
	v_add_f32_e32 v12, v12, v19
	v_addc_co_u32_e32 v19, vcc, 0, v17, vcc
	v_cvt_pk_bf16_f32 v2, v2, v12
	global_store_dword v[18:19], v2, off
.LBB0_1980:
	s_or_b64 exec, exec, s[10:11]
	v_mul_f32_e32 v2, v55, v13
	s_nop 1
	v_mov_b32_dpp v12, v2 quad_perm:[1,0,3,2] row_mask:0xf bank_mask:0xf bound_ctrl:1
	s_and_saveexec_b64 s[10:11], s[8:9]
	s_cbranch_execz .LBB0_1982
	v_mov_b32_e32 v19, v216
	v_add_co_u32_e32 v18, vcc, 0x12000, v16
	v_lshlrev_b32_e32 v20, 16, v19
	v_and_b32_e32 v19, 0xffff0000, v19
	v_add_f32_e32 v2, v2, v20
	v_add_f32_e32 v12, v12, v19
	v_addc_co_u32_e32 v19, vcc, 0, v17, vcc
	v_cvt_pk_bf16_f32 v2, v2, v12
	global_store_dword v[18:19], v2, off offset:64
.LBB0_1982:
	s_or_b64 exec, exec, s[10:11]
	v_mul_f32_e32 v2, v39, v13
	s_nop 1
	v_mov_b32_dpp v12, v2 quad_perm:[1,0,3,2] row_mask:0xf bank_mask:0xf bound_ctrl:1
	s_and_saveexec_b64 s[10:11], s[8:9]
	s_cbranch_execz .LBB0_1984
	v_mov_b32_e32 v19, v217
	v_add_co_u32_e32 v18, vcc, 0x12000, v16
	v_lshlrev_b32_e32 v20, 16, v19
	v_and_b32_e32 v19, 0xffff0000, v19
	v_add_f32_e32 v2, v2, v20
	v_add_f32_e32 v12, v12, v19
	v_addc_co_u32_e32 v19, vcc, 0, v17, vcc
	v_cvt_pk_bf16_f32 v2, v2, v12
	global_store_dword v[18:19], v2, off offset:128
.LBB0_1984:
	s_or_b64 exec, exec, s[10:11]
	v_mul_f32_e32 v2, v23, v13
	s_nop 1
	v_mov_b32_dpp v12, v2 quad_perm:[1,0,3,2] row_mask:0xf bank_mask:0xf bound_ctrl:1
	s_and_saveexec_b64 s[10:11], s[8:9]
	s_cbranch_execz .LBB0_1986
	v_mov_b32_e32 v13, v218
	v_add_co_u32_e32 v18, vcc, 0x12000, v16
	v_lshlrev_b32_e32 v19, 16, v13
	v_and_b32_e32 v13, 0xffff0000, v13
	v_add_f32_e32 v2, v2, v19
	v_addc_co_u32_e32 v19, vcc, 0, v17, vcc
	v_add_f32_e32 v12, v12, v13
	v_cvt_pk_bf16_f32 v2, v2, v12
	global_store_dword v[18:19], v2, off offset:192
.LBB0_1986:
	s_or_b64 exec, exec, s[10:11]
	v_mul_f32_e32 v2, v72, v14
	s_nop 1
	v_mov_b32_dpp v12, v2 quad_perm:[1,0,3,2] row_mask:0xf bank_mask:0xf bound_ctrl:1
	s_and_saveexec_b64 s[10:11], s[8:9]
	s_cbranch_execz .LBB0_1988
	v_mov_b32_e32 v13, v219
	v_add_co_u32_e32 v18, vcc, 0x14000, v16
	v_lshlrev_b32_e32 v19, 16, v13
	v_and_b32_e32 v13, 0xffff0000, v13
	v_add_f32_e32 v2, v2, v19
	v_addc_co_u32_e32 v19, vcc, 0, v17, vcc
	v_add_f32_e32 v12, v12, v13
	v_cvt_pk_bf16_f32 v2, v2, v12
	global_store_dword v[18:19], v2, off
.LBB0_1988:
	s_or_b64 exec, exec, s[10:11]
	v_mul_f32_e32 v2, v56, v14
	s_nop 1
	v_mov_b32_dpp v12, v2 quad_perm:[1,0,3,2] row_mask:0xf bank_mask:0xf bound_ctrl:1
	s_and_saveexec_b64 s[10:11], s[8:9]
	s_cbranch_execz .LBB0_1990
	v_mov_b32_e32 v13, v220
	v_add_co_u32_e32 v18, vcc, 0x14000, v16
	v_lshlrev_b32_e32 v19, 16, v13
	v_and_b32_e32 v13, 0xffff0000, v13
	v_add_f32_e32 v2, v2, v19
	v_addc_co_u32_e32 v19, vcc, 0, v17, vcc
	v_add_f32_e32 v12, v12, v13
	v_cvt_pk_bf16_f32 v2, v2, v12
	global_store_dword v[18:19], v2, off offset:64
.LBB0_1990:
	s_or_b64 exec, exec, s[10:11]
	v_mul_f32_e32 v2, v40, v14
	s_nop 1
	v_mov_b32_dpp v12, v2 quad_perm:[1,0,3,2] row_mask:0xf bank_mask:0xf bound_ctrl:1
	s_and_saveexec_b64 s[10:11], s[8:9]
	s_cbranch_execz .LBB0_1992
	v_mov_b32_e32 v13, v221
	v_add_co_u32_e32 v18, vcc, 0x14000, v16
	v_lshlrev_b32_e32 v19, 16, v13
	v_and_b32_e32 v13, 0xffff0000, v13
	v_add_f32_e32 v2, v2, v19
	v_addc_co_u32_e32 v19, vcc, 0, v17, vcc
	v_add_f32_e32 v12, v12, v13
	v_cvt_pk_bf16_f32 v2, v2, v12
	global_store_dword v[18:19], v2, off offset:128
.LBB0_1992:
	s_or_b64 exec, exec, s[10:11]
	v_mul_f32_e32 v2, v24, v14
	s_nop 1
	v_mov_b32_dpp v12, v2 quad_perm:[1,0,3,2] row_mask:0xf bank_mask:0xf bound_ctrl:1
	s_and_saveexec_b64 s[10:11], s[8:9]
	s_cbranch_execz .LBB0_1994
	v_mov_b32_e32 v13, v222
	v_add_co_u32_e32 v18, vcc, 0x14000, v16
	v_lshlrev_b32_e32 v14, 16, v13
	v_and_b32_e32 v13, 0xffff0000, v13
	v_add_f32_e32 v2, v2, v14
	v_addc_co_u32_e32 v19, vcc, 0, v17, vcc
	v_add_f32_e32 v12, v12, v13
	v_cvt_pk_bf16_f32 v2, v2, v12
	global_store_dword v[18:19], v2, off offset:192
.LBB0_1994:
	s_or_b64 exec, exec, s[10:11]
	v_mul_f32_e32 v2, v73, v15
	s_nop 1
	v_mov_b32_dpp v12, v2 quad_perm:[1,0,3,2] row_mask:0xf bank_mask:0xf bound_ctrl:1
	s_and_saveexec_b64 s[10:11], s[8:9]
	s_cbranch_execz .LBB0_1996
	v_mov_b32_e32 v13, v223
	v_add_co_u32_e32 v18, vcc, 0x16000, v16
	v_lshlrev_b32_e32 v14, 16, v13
	v_and_b32_e32 v13, 0xffff0000, v13
	v_add_f32_e32 v2, v2, v14
	v_addc_co_u32_e32 v19, vcc, 0, v17, vcc
	v_add_f32_e32 v12, v12, v13
	v_cvt_pk_bf16_f32 v2, v2, v12
	global_store_dword v[18:19], v2, off
.LBB0_1996:
	s_or_b64 exec, exec, s[10:11]
	v_mul_f32_e32 v2, v57, v15
	s_nop 1
	v_mov_b32_dpp v12, v2 quad_perm:[1,0,3,2] row_mask:0xf bank_mask:0xf bound_ctrl:1
	s_and_saveexec_b64 s[10:11], s[8:9]
	s_cbranch_execz .LBB0_1998
	v_mov_b32_e32 v13, v224
	v_add_co_u32_e32 v18, vcc, 0x16000, v16
	v_lshlrev_b32_e32 v14, 16, v13
	v_and_b32_e32 v13, 0xffff0000, v13
	v_add_f32_e32 v2, v2, v14
	v_addc_co_u32_e32 v19, vcc, 0, v17, vcc
	v_add_f32_e32 v12, v12, v13
	v_cvt_pk_bf16_f32 v2, v2, v12
	global_store_dword v[18:19], v2, off offset:64
.LBB0_1998:
	s_or_b64 exec, exec, s[10:11]
	v_mul_f32_e32 v2, v41, v15
	s_nop 1
	v_mov_b32_dpp v12, v2 quad_perm:[1,0,3,2] row_mask:0xf bank_mask:0xf bound_ctrl:1
	s_and_saveexec_b64 s[10:11], s[8:9]
	s_cbranch_execz .LBB0_2000
	v_mov_b32_e32 v13, v225
	v_add_co_u32_e32 v18, vcc, 0x16000, v16
	v_lshlrev_b32_e32 v14, 16, v13
	v_and_b32_e32 v13, 0xffff0000, v13
	v_add_f32_e32 v2, v2, v14
	v_addc_co_u32_e32 v19, vcc, 0, v17, vcc
	v_add_f32_e32 v12, v12, v13
	v_cvt_pk_bf16_f32 v2, v2, v12
	global_store_dword v[18:19], v2, off offset:128
.LBB0_2000:
	s_or_b64 exec, exec, s[10:11]
	v_mul_f32_e32 v2, v25, v15
	s_nop 1
	v_mov_b32_dpp v12, v2 quad_perm:[1,0,3,2] row_mask:0xf bank_mask:0xf bound_ctrl:1
	s_and_saveexec_b64 s[10:11], s[8:9]
	s_cbranch_execz .LBB0_2002
	v_mov_b32_e32 v13, v226
	v_add_co_u32_e32 v14, vcc, 0x16000, v16
	v_lshlrev_b32_e32 v15, 16, v13
	v_and_b32_e32 v13, 0xffff0000, v13
	v_add_f32_e32 v2, v2, v15
	v_addc_co_u32_e32 v15, vcc, 0, v17, vcc
	v_add_f32_e32 v12, v12, v13
	v_cvt_pk_bf16_f32 v2, v2, v12
	global_store_dword v[14:15], v2, off offset:192
.LBB0_2002:
	s_or_b64 exec, exec, s[10:11]
	v_mul_f32_e32 v2, v74, v8
	s_nop 1
	v_mov_b32_dpp v12, v2 quad_perm:[1,0,3,2] row_mask:0xf bank_mask:0xf bound_ctrl:1
	s_and_saveexec_b64 s[10:11], s[8:9]
	s_cbranch_execz .LBB0_2004
	v_mov_b32_e32 v13, v227
	v_add_co_u32_e32 v14, vcc, 0x20000, v16
	v_lshlrev_b32_e32 v15, 16, v13
	v_and_b32_e32 v13, 0xffff0000, v13
	v_add_f32_e32 v2, v2, v15
	v_addc_co_u32_e32 v15, vcc, 0, v17, vcc
	v_add_f32_e32 v12, v12, v13
	v_cvt_pk_bf16_f32 v2, v2, v12
	global_store_dword v[14:15], v2, off
.LBB0_2004:
	s_or_b64 exec, exec, s[10:11]
	v_mul_f32_e32 v2, v58, v8
	s_nop 1
	v_mov_b32_dpp v12, v2 quad_perm:[1,0,3,2] row_mask:0xf bank_mask:0xf bound_ctrl:1
	s_and_saveexec_b64 s[10:11], s[8:9]
	s_cbranch_execz .LBB0_2006
	v_mov_b32_e32 v13, v228
	v_add_co_u32_e32 v14, vcc, 0x20000, v16
	v_lshlrev_b32_e32 v15, 16, v13
	v_and_b32_e32 v13, 0xffff0000, v13
	v_add_f32_e32 v2, v2, v15
	v_addc_co_u32_e32 v15, vcc, 0, v17, vcc
	v_add_f32_e32 v12, v12, v13
	v_cvt_pk_bf16_f32 v2, v2, v12
	global_store_dword v[14:15], v2, off offset:64
.LBB0_2006:
	s_or_b64 exec, exec, s[10:11]
	v_mul_f32_e32 v2, v42, v8
	s_nop 1
	v_mov_b32_dpp v12, v2 quad_perm:[1,0,3,2] row_mask:0xf bank_mask:0xf bound_ctrl:1
	s_and_saveexec_b64 s[10:11], s[8:9]
	s_cbranch_execz .LBB0_2008
	v_mov_b32_e32 v13, v229
	v_add_co_u32_e32 v14, vcc, 0x20000, v16
	v_lshlrev_b32_e32 v15, 16, v13
	v_and_b32_e32 v13, 0xffff0000, v13
	v_add_f32_e32 v2, v2, v15
	v_addc_co_u32_e32 v15, vcc, 0, v17, vcc
	v_add_f32_e32 v12, v12, v13
	v_cvt_pk_bf16_f32 v2, v2, v12
	global_store_dword v[14:15], v2, off offset:128
.LBB0_2008:
	s_or_b64 exec, exec, s[10:11]
	v_mul_f32_e32 v2, v26, v8
	s_nop 1
	v_mov_b32_dpp v8, v2 quad_perm:[1,0,3,2] row_mask:0xf bank_mask:0xf bound_ctrl:1
	s_and_saveexec_b64 s[10:11], s[8:9]
	s_cbranch_execz .LBB0_2010
	v_mov_b32_e32 v13, v230
	v_add_co_u32_e32 v12, vcc, 0x20000, v16
	v_lshlrev_b32_e32 v14, 16, v13
	v_and_b32_e32 v13, 0xffff0000, v13
	v_add_f32_e32 v2, v2, v14
	v_add_f32_e32 v8, v8, v13
	v_addc_co_u32_e32 v13, vcc, 0, v17, vcc
	v_cvt_pk_bf16_f32 v2, v2, v8
	global_store_dword v[12:13], v2, off offset:192
.LBB0_2010:
	s_or_b64 exec, exec, s[10:11]
	v_mul_f32_e32 v2, v75, v9
	s_nop 1
	v_mov_b32_dpp v8, v2 quad_perm:[1,0,3,2] row_mask:0xf bank_mask:0xf bound_ctrl:1
	s_and_saveexec_b64 s[10:11], s[8:9]
	s_cbranch_execz .LBB0_2012
	v_mov_b32_e32 v13, v231
	v_add_co_u32_e32 v12, vcc, 0x22000, v16
	v_lshlrev_b32_e32 v14, 16, v13
	v_and_b32_e32 v13, 0xffff0000, v13
	v_add_f32_e32 v2, v2, v14
	v_add_f32_e32 v8, v8, v13
	v_addc_co_u32_e32 v13, vcc, 0, v17, vcc
	v_cvt_pk_bf16_f32 v2, v2, v8
	global_store_dword v[12:13], v2, off
.LBB0_2012:
	s_or_b64 exec, exec, s[10:11]
	v_mul_f32_e32 v2, v59, v9
	s_nop 1
	v_mov_b32_dpp v8, v2 quad_perm:[1,0,3,2] row_mask:0xf bank_mask:0xf bound_ctrl:1
	s_and_saveexec_b64 s[10:11], s[8:9]
	s_cbranch_execz .LBB0_2014
	v_mov_b32_e32 v13, v232
	v_add_co_u32_e32 v12, vcc, 0x22000, v16
	v_lshlrev_b32_e32 v14, 16, v13
	v_and_b32_e32 v13, 0xffff0000, v13
	v_add_f32_e32 v2, v2, v14
	v_add_f32_e32 v8, v8, v13
	v_addc_co_u32_e32 v13, vcc, 0, v17, vcc
	v_cvt_pk_bf16_f32 v2, v2, v8
	global_store_dword v[12:13], v2, off offset:64
.LBB0_2014:
	s_or_b64 exec, exec, s[10:11]
	v_mul_f32_e32 v2, v43, v9
	s_nop 1
	v_mov_b32_dpp v8, v2 quad_perm:[1,0,3,2] row_mask:0xf bank_mask:0xf bound_ctrl:1
	s_and_saveexec_b64 s[10:11], s[8:9]
	s_cbranch_execz .LBB0_2016
	v_mov_b32_e32 v13, v233
	v_add_co_u32_e32 v12, vcc, 0x22000, v16
	v_lshlrev_b32_e32 v14, 16, v13
	v_and_b32_e32 v13, 0xffff0000, v13
	v_add_f32_e32 v2, v2, v14
	v_add_f32_e32 v8, v8, v13
	v_addc_co_u32_e32 v13, vcc, 0, v17, vcc
	v_cvt_pk_bf16_f32 v2, v2, v8
	global_store_dword v[12:13], v2, off offset:128
.LBB0_2016:
	s_or_b64 exec, exec, s[10:11]
	v_mul_f32_e32 v2, v27, v9
	s_nop 1
	v_mov_b32_dpp v8, v2 quad_perm:[1,0,3,2] row_mask:0xf bank_mask:0xf bound_ctrl:1
	s_and_saveexec_b64 s[10:11], s[8:9]
	s_cbranch_execz .LBB0_2018
	v_mov_b32_e32 v9, v234
	v_add_co_u32_e32 v12, vcc, 0x22000, v16
	v_lshlrev_b32_e32 v13, 16, v9
	v_and_b32_e32 v9, 0xffff0000, v9
	v_add_f32_e32 v2, v2, v13
	v_addc_co_u32_e32 v13, vcc, 0, v17, vcc
	v_add_f32_e32 v8, v8, v9
	v_cvt_pk_bf16_f32 v2, v2, v8
	global_store_dword v[12:13], v2, off offset:192
.LBB0_2018:
	s_or_b64 exec, exec, s[10:11]
	v_mul_f32_e32 v2, v76, v10
	s_nop 1
	v_mov_b32_dpp v8, v2 quad_perm:[1,0,3,2] row_mask:0xf bank_mask:0xf bound_ctrl:1
	s_and_saveexec_b64 s[10:11], s[8:9]
	s_cbranch_execz .LBB0_2020
	v_mov_b32_e32 v9, v235
	v_add_co_u32_e32 v12, vcc, 0x24000, v16
	v_lshlrev_b32_e32 v13, 16, v9
	v_and_b32_e32 v9, 0xffff0000, v9
	v_add_f32_e32 v2, v2, v13
	v_addc_co_u32_e32 v13, vcc, 0, v17, vcc
	v_add_f32_e32 v8, v8, v9
	v_cvt_pk_bf16_f32 v2, v2, v8
	global_store_dword v[12:13], v2, off
.LBB0_2020:
	s_or_b64 exec, exec, s[10:11]
	v_mul_f32_e32 v2, v60, v10
	s_nop 1
	v_mov_b32_dpp v8, v2 quad_perm:[1,0,3,2] row_mask:0xf bank_mask:0xf bound_ctrl:1
	s_and_saveexec_b64 s[10:11], s[8:9]
	s_cbranch_execz .LBB0_2022
	v_mov_b32_e32 v9, v236
	v_add_co_u32_e32 v12, vcc, 0x24000, v16
	v_lshlrev_b32_e32 v13, 16, v9
	v_and_b32_e32 v9, 0xffff0000, v9
	v_add_f32_e32 v2, v2, v13
	v_addc_co_u32_e32 v13, vcc, 0, v17, vcc
	v_add_f32_e32 v8, v8, v9
	v_cvt_pk_bf16_f32 v2, v2, v8
	global_store_dword v[12:13], v2, off offset:64
.LBB0_2022:
	s_or_b64 exec, exec, s[10:11]
	v_mul_f32_e32 v2, v44, v10
	s_nop 1
	v_mov_b32_dpp v8, v2 quad_perm:[1,0,3,2] row_mask:0xf bank_mask:0xf bound_ctrl:1
	s_and_saveexec_b64 s[10:11], s[8:9]
	s_cbranch_execz .LBB0_2024
	v_mov_b32_e32 v9, v237
	v_add_co_u32_e32 v12, vcc, 0x24000, v16
	v_lshlrev_b32_e32 v13, 16, v9
	v_and_b32_e32 v9, 0xffff0000, v9
	v_add_f32_e32 v2, v2, v13
	v_addc_co_u32_e32 v13, vcc, 0, v17, vcc
	v_add_f32_e32 v8, v8, v9
	v_cvt_pk_bf16_f32 v2, v2, v8
	global_store_dword v[12:13], v2, off offset:128
.LBB0_2024:
	s_or_b64 exec, exec, s[10:11]
	v_mul_f32_e32 v2, v28, v10
	s_nop 1
	v_mov_b32_dpp v8, v2 quad_perm:[1,0,3,2] row_mask:0xf bank_mask:0xf bound_ctrl:1
	s_and_saveexec_b64 s[10:11], s[8:9]
	s_cbranch_execz .LBB0_2026
	v_mov_b32_e32 v9, v238
	v_add_co_u32_e32 v12, vcc, 0x24000, v16
	v_lshlrev_b32_e32 v10, 16, v9
	v_and_b32_e32 v9, 0xffff0000, v9
	v_add_f32_e32 v2, v2, v10
	v_addc_co_u32_e32 v13, vcc, 0, v17, vcc
	v_add_f32_e32 v8, v8, v9
	v_cvt_pk_bf16_f32 v2, v2, v8
	global_store_dword v[12:13], v2, off offset:192
.LBB0_2026:
	s_or_b64 exec, exec, s[10:11]
	v_mul_f32_e32 v2, v77, v11
	s_nop 1
	v_mov_b32_dpp v8, v2 quad_perm:[1,0,3,2] row_mask:0xf bank_mask:0xf bound_ctrl:1
	s_and_saveexec_b64 s[10:11], s[8:9]
	s_cbranch_execz .LBB0_2028
	v_mov_b32_e32 v9, v239
	v_add_co_u32_e32 v12, vcc, 0x26000, v16
	v_lshlrev_b32_e32 v10, 16, v9
	v_and_b32_e32 v9, 0xffff0000, v9
	v_add_f32_e32 v2, v2, v10
	v_addc_co_u32_e32 v13, vcc, 0, v17, vcc
	v_add_f32_e32 v8, v8, v9
	v_cvt_pk_bf16_f32 v2, v2, v8
	global_store_dword v[12:13], v2, off
.LBB0_2028:
	s_or_b64 exec, exec, s[10:11]
	v_mul_f32_e32 v2, v61, v11
	s_nop 1
	v_mov_b32_dpp v8, v2 quad_perm:[1,0,3,2] row_mask:0xf bank_mask:0xf bound_ctrl:1
	s_and_saveexec_b64 s[10:11], s[8:9]
	s_cbranch_execz .LBB0_2030
	v_mov_b32_e32 v9, v92
	v_add_co_u32_e32 v12, vcc, 0x26000, v16
	v_lshlrev_b32_e32 v10, 16, v9
	v_and_b32_e32 v9, 0xffff0000, v9
	v_add_f32_e32 v2, v2, v10
	v_addc_co_u32_e32 v13, vcc, 0, v17, vcc
	v_add_f32_e32 v8, v8, v9
	v_cvt_pk_bf16_f32 v2, v2, v8
	global_store_dword v[12:13], v2, off offset:64
.LBB0_2030:
	s_or_b64 exec, exec, s[10:11]
	v_mul_f32_e32 v2, v45, v11
	s_nop 1
	v_mov_b32_dpp v8, v2 quad_perm:[1,0,3,2] row_mask:0xf bank_mask:0xf bound_ctrl:1
	s_and_saveexec_b64 s[10:11], s[8:9]
	s_cbranch_execz .LBB0_2032
	v_mov_b32_e32 v9, v93
	v_add_co_u32_e32 v12, vcc, 0x26000, v16
	v_lshlrev_b32_e32 v10, 16, v9
	v_and_b32_e32 v9, 0xffff0000, v9
	v_add_f32_e32 v2, v2, v10
	v_addc_co_u32_e32 v13, vcc, 0, v17, vcc
	v_add_f32_e32 v8, v8, v9
	v_cvt_pk_bf16_f32 v2, v2, v8
	global_store_dword v[12:13], v2, off offset:128
.LBB0_2032:
	s_or_b64 exec, exec, s[10:11]
	v_mul_f32_e32 v2, v29, v11
	s_nop 1
	v_mov_b32_dpp v8, v2 quad_perm:[1,0,3,2] row_mask:0xf bank_mask:0xf bound_ctrl:1
	s_and_saveexec_b64 s[10:11], s[8:9]
	s_cbranch_execz .LBB0_2034
	v_mov_b32_e32 v9, v94
	v_add_co_u32_e32 v10, vcc, 0x26000, v16
	v_lshlrev_b32_e32 v11, 16, v9
	v_and_b32_e32 v9, 0xffff0000, v9
	v_add_f32_e32 v2, v2, v11
	v_addc_co_u32_e32 v11, vcc, 0, v17, vcc
	v_add_f32_e32 v8, v8, v9
	v_cvt_pk_bf16_f32 v2, v2, v8
	global_store_dword v[10:11], v2, off offset:192
.LBB0_2034:
	s_or_b64 exec, exec, s[10:11]
	v_mul_f32_e32 v2, v78, v4
	s_nop 1
	v_mov_b32_dpp v8, v2 quad_perm:[1,0,3,2] row_mask:0xf bank_mask:0xf bound_ctrl:1
	s_and_saveexec_b64 s[10:11], s[8:9]
	s_cbranch_execz .LBB0_2036
	v_mov_b32_e32 v9, v95
	v_add_co_u32_e32 v10, vcc, 0x30000, v16
	v_lshlrev_b32_e32 v11, 16, v9
	v_and_b32_e32 v9, 0xffff0000, v9
	v_add_f32_e32 v2, v2, v11
	v_addc_co_u32_e32 v11, vcc, 0, v17, vcc
	v_add_f32_e32 v8, v8, v9
	v_cvt_pk_bf16_f32 v2, v2, v8
	global_store_dword v[10:11], v2, off
.LBB0_2036:
	s_or_b64 exec, exec, s[10:11]
	v_mul_f32_e32 v2, v62, v4
	s_nop 1
	v_mov_b32_dpp v8, v2 quad_perm:[1,0,3,2] row_mask:0xf bank_mask:0xf bound_ctrl:1
	s_and_saveexec_b64 s[10:11], s[8:9]
	s_cbranch_execz .LBB0_2038
	v_mov_b32_e32 v9, v96
	v_add_co_u32_e32 v10, vcc, 0x30000, v16
	v_lshlrev_b32_e32 v11, 16, v9
	v_and_b32_e32 v9, 0xffff0000, v9
	v_add_f32_e32 v2, v2, v11
	v_addc_co_u32_e32 v11, vcc, 0, v17, vcc
	v_add_f32_e32 v8, v8, v9
	v_cvt_pk_bf16_f32 v2, v2, v8
	global_store_dword v[10:11], v2, off offset:64
.LBB0_2038:
	s_or_b64 exec, exec, s[10:11]
	v_mul_f32_e32 v2, v46, v4
	s_nop 1
	v_mov_b32_dpp v8, v2 quad_perm:[1,0,3,2] row_mask:0xf bank_mask:0xf bound_ctrl:1
	s_and_saveexec_b64 s[10:11], s[8:9]
	s_cbranch_execz .LBB0_2040
	v_mov_b32_e32 v9, v97
	v_add_co_u32_e32 v10, vcc, 0x30000, v16
	v_lshlrev_b32_e32 v11, 16, v9
	v_and_b32_e32 v9, 0xffff0000, v9
	v_add_f32_e32 v2, v2, v11
	v_addc_co_u32_e32 v11, vcc, 0, v17, vcc
	v_add_f32_e32 v8, v8, v9
	v_cvt_pk_bf16_f32 v2, v2, v8
	global_store_dword v[10:11], v2, off offset:128
.LBB0_2040:
	s_or_b64 exec, exec, s[10:11]
	v_mul_f32_e32 v2, v30, v4
	s_nop 1
	v_mov_b32_dpp v4, v2 quad_perm:[1,0,3,2] row_mask:0xf bank_mask:0xf bound_ctrl:1
	s_and_saveexec_b64 s[10:11], s[8:9]
	s_cbranch_execz .LBB0_2042
	v_mov_b32_e32 v9, v98
	v_add_co_u32_e32 v8, vcc, 0x30000, v16
	v_lshlrev_b32_e32 v10, 16, v9
	v_and_b32_e32 v9, 0xffff0000, v9
	v_add_f32_e32 v2, v2, v10
	v_add_f32_e32 v4, v4, v9
	v_addc_co_u32_e32 v9, vcc, 0, v17, vcc
	v_cvt_pk_bf16_f32 v2, v2, v4
	global_store_dword v[8:9], v2, off offset:192
.LBB0_2042:
	s_or_b64 exec, exec, s[10:11]
	v_mul_f32_e32 v2, v79, v5
	s_nop 1
	v_mov_b32_dpp v4, v2 quad_perm:[1,0,3,2] row_mask:0xf bank_mask:0xf bound_ctrl:1
	s_and_saveexec_b64 s[10:11], s[8:9]
	s_cbranch_execz .LBB0_2044
	v_mov_b32_e32 v9, v99
	v_add_co_u32_e32 v8, vcc, 0x32000, v16
	v_lshlrev_b32_e32 v10, 16, v9
	v_and_b32_e32 v9, 0xffff0000, v9
	v_add_f32_e32 v2, v2, v10
	v_add_f32_e32 v4, v4, v9
	v_addc_co_u32_e32 v9, vcc, 0, v17, vcc
	v_cvt_pk_bf16_f32 v2, v2, v4
	global_store_dword v[8:9], v2, off
.LBB0_2044:
	s_or_b64 exec, exec, s[10:11]
	v_mul_f32_e32 v2, v63, v5
	s_nop 1
	v_mov_b32_dpp v4, v2 quad_perm:[1,0,3,2] row_mask:0xf bank_mask:0xf bound_ctrl:1
	s_and_saveexec_b64 s[10:11], s[8:9]
	s_cbranch_execz .LBB0_2046
	v_mov_b32_e32 v9, v100
	v_add_co_u32_e32 v8, vcc, 0x32000, v16
	v_lshlrev_b32_e32 v10, 16, v9
	v_and_b32_e32 v9, 0xffff0000, v9
	v_add_f32_e32 v2, v2, v10
	v_add_f32_e32 v4, v4, v9
	v_addc_co_u32_e32 v9, vcc, 0, v17, vcc
	v_cvt_pk_bf16_f32 v2, v2, v4
	global_store_dword v[8:9], v2, off offset:64
.LBB0_2046:
	s_or_b64 exec, exec, s[10:11]
	v_mul_f32_e32 v2, v47, v5
	s_nop 1
	v_mov_b32_dpp v4, v2 quad_perm:[1,0,3,2] row_mask:0xf bank_mask:0xf bound_ctrl:1
	s_and_saveexec_b64 s[10:11], s[8:9]
	s_cbranch_execz .LBB0_2048
	v_mov_b32_e32 v9, v101
	v_add_co_u32_e32 v8, vcc, 0x32000, v16
	v_lshlrev_b32_e32 v10, 16, v9
	v_and_b32_e32 v9, 0xffff0000, v9
	v_add_f32_e32 v2, v2, v10
	v_add_f32_e32 v4, v4, v9
	v_addc_co_u32_e32 v9, vcc, 0, v17, vcc
	v_cvt_pk_bf16_f32 v2, v2, v4
	global_store_dword v[8:9], v2, off offset:128
.LBB0_2048:
	s_or_b64 exec, exec, s[10:11]
	v_mul_f32_e32 v2, v31, v5
	s_nop 1
	v_mov_b32_dpp v4, v2 quad_perm:[1,0,3,2] row_mask:0xf bank_mask:0xf bound_ctrl:1
	s_and_saveexec_b64 s[10:11], s[8:9]
	s_cbranch_execz .LBB0_2050
	v_mov_b32_e32 v5, v102
	v_add_co_u32_e32 v8, vcc, 0x32000, v16
	v_lshlrev_b32_e32 v9, 16, v5
	v_and_b32_e32 v5, 0xffff0000, v5
	v_add_f32_e32 v2, v2, v9
	v_addc_co_u32_e32 v9, vcc, 0, v17, vcc
	v_add_f32_e32 v4, v4, v5
	v_cvt_pk_bf16_f32 v2, v2, v4
	global_store_dword v[8:9], v2, off offset:192
.LBB0_2050:
	s_or_b64 exec, exec, s[10:11]
	v_mul_f32_e32 v2, v80, v6
	s_nop 1
	v_mov_b32_dpp v4, v2 quad_perm:[1,0,3,2] row_mask:0xf bank_mask:0xf bound_ctrl:1
	s_and_saveexec_b64 s[10:11], s[8:9]
	s_cbranch_execz .LBB0_2052
	v_mov_b32_e32 v5, v103
	v_add_co_u32_e32 v8, vcc, 0x34000, v16
	v_lshlrev_b32_e32 v9, 16, v5
	v_and_b32_e32 v5, 0xffff0000, v5
	v_add_f32_e32 v2, v2, v9
	v_addc_co_u32_e32 v9, vcc, 0, v17, vcc
	v_add_f32_e32 v4, v4, v5
	v_cvt_pk_bf16_f32 v2, v2, v4
	global_store_dword v[8:9], v2, off
.LBB0_2052:
	s_or_b64 exec, exec, s[10:11]
	v_mul_f32_e32 v2, v64, v6
	s_nop 1
	v_mov_b32_dpp v4, v2 quad_perm:[1,0,3,2] row_mask:0xf bank_mask:0xf bound_ctrl:1
	s_and_saveexec_b64 s[10:11], s[8:9]
	s_cbranch_execz .LBB0_2054
	v_mov_b32_e32 v5, v104
	v_add_co_u32_e32 v8, vcc, 0x34000, v16
	v_lshlrev_b32_e32 v9, 16, v5
	v_and_b32_e32 v5, 0xffff0000, v5
	v_add_f32_e32 v2, v2, v9
	v_addc_co_u32_e32 v9, vcc, 0, v17, vcc
	v_add_f32_e32 v4, v4, v5
	v_cvt_pk_bf16_f32 v2, v2, v4
	global_store_dword v[8:9], v2, off offset:64
.LBB0_2054:
	s_or_b64 exec, exec, s[10:11]
	v_mul_f32_e32 v2, v48, v6
	s_nop 1
	v_mov_b32_dpp v4, v2 quad_perm:[1,0,3,2] row_mask:0xf bank_mask:0xf bound_ctrl:1
	s_and_saveexec_b64 s[10:11], s[8:9]
	s_cbranch_execz .LBB0_2056
	v_mov_b32_e32 v5, v105
	v_add_co_u32_e32 v8, vcc, 0x34000, v16
	v_lshlrev_b32_e32 v9, 16, v5
	v_and_b32_e32 v5, 0xffff0000, v5
	v_add_f32_e32 v2, v2, v9
	v_addc_co_u32_e32 v9, vcc, 0, v17, vcc
	v_add_f32_e32 v4, v4, v5
	v_cvt_pk_bf16_f32 v2, v2, v4
	global_store_dword v[8:9], v2, off offset:128
.LBB0_2056:
	s_or_b64 exec, exec, s[10:11]
	v_mul_f32_e32 v2, v32, v6
	s_nop 1
	v_mov_b32_dpp v4, v2 quad_perm:[1,0,3,2] row_mask:0xf bank_mask:0xf bound_ctrl:1
	s_and_saveexec_b64 s[10:11], s[8:9]
	s_cbranch_execz .LBB0_2058
	v_mov_b32_e32 v5, v106
	v_add_co_u32_e32 v8, vcc, 0x34000, v16
	v_lshlrev_b32_e32 v6, 16, v5
	v_and_b32_e32 v5, 0xffff0000, v5
	v_add_f32_e32 v2, v2, v6
	v_addc_co_u32_e32 v9, vcc, 0, v17, vcc
	v_add_f32_e32 v4, v4, v5
	v_cvt_pk_bf16_f32 v2, v2, v4
	global_store_dword v[8:9], v2, off offset:192
.LBB0_2058:
	s_or_b64 exec, exec, s[10:11]
	v_mul_f32_e32 v2, v81, v7
	s_nop 1
	v_mov_b32_dpp v4, v2 quad_perm:[1,0,3,2] row_mask:0xf bank_mask:0xf bound_ctrl:1
	s_and_saveexec_b64 s[10:11], s[8:9]
	s_cbranch_execz .LBB0_2060
	v_mov_b32_e32 v5, v107
	v_add_co_u32_e32 v8, vcc, 0x36000, v16
	v_lshlrev_b32_e32 v6, 16, v5
	v_and_b32_e32 v5, 0xffff0000, v5
	v_add_f32_e32 v2, v2, v6
	v_addc_co_u32_e32 v9, vcc, 0, v17, vcc
	v_add_f32_e32 v4, v4, v5
	v_cvt_pk_bf16_f32 v2, v2, v4
	global_store_dword v[8:9], v2, off
.LBB0_2060:
	s_or_b64 exec, exec, s[10:11]
	v_mul_f32_e32 v2, v65, v7
	s_nop 1
	v_mov_b32_dpp v4, v2 quad_perm:[1,0,3,2] row_mask:0xf bank_mask:0xf bound_ctrl:1
	s_and_saveexec_b64 s[10:11], s[8:9]
	s_cbranch_execz .LBB0_2062
	v_mov_b32_e32 v5, v108
	v_add_co_u32_e32 v8, vcc, 0x36000, v16
	v_lshlrev_b32_e32 v6, 16, v5
	v_and_b32_e32 v5, 0xffff0000, v5
	v_add_f32_e32 v2, v2, v6
	v_addc_co_u32_e32 v9, vcc, 0, v17, vcc
	v_add_f32_e32 v4, v4, v5
	v_cvt_pk_bf16_f32 v2, v2, v4
	global_store_dword v[8:9], v2, off offset:64
.LBB0_2062:
	s_or_b64 exec, exec, s[10:11]
	v_mul_f32_e32 v2, v49, v7
	s_nop 1
	v_mov_b32_dpp v4, v2 quad_perm:[1,0,3,2] row_mask:0xf bank_mask:0xf bound_ctrl:1
	s_and_saveexec_b64 s[10:11], s[8:9]
	s_cbranch_execz .LBB0_2064
	v_mov_b32_e32 v5, v109
	v_add_co_u32_e32 v8, vcc, 0x36000, v16
	v_lshlrev_b32_e32 v6, 16, v5
	v_and_b32_e32 v5, 0xffff0000, v5
	v_add_f32_e32 v2, v2, v6
	v_addc_co_u32_e32 v9, vcc, 0, v17, vcc
	v_add_f32_e32 v4, v4, v5
	v_cvt_pk_bf16_f32 v2, v2, v4
	global_store_dword v[8:9], v2, off offset:128
.LBB0_2064:
	s_or_b64 exec, exec, s[10:11]
	v_mul_f32_e32 v2, v33, v7
	s_nop 1
	v_mov_b32_dpp v4, v2 quad_perm:[1,0,3,2] row_mask:0xf bank_mask:0xf bound_ctrl:1
	s_and_saveexec_b64 s[10:11], s[8:9]
	s_cbranch_execz .LBB0_1473
	v_mov_b32_e32 v5, v110
	v_add_co_u32_e32 v6, vcc, 0x36000, v16
	v_lshlrev_b32_e32 v7, 16, v5
	v_and_b32_e32 v5, 0xffff0000, v5
	v_add_f32_e32 v2, v2, v7
	v_addc_co_u32_e32 v7, vcc, 0, v17, vcc
	v_add_f32_e32 v4, v4, v5
	v_cvt_pk_bf16_f32 v2, v2, v4
	global_store_dword v[6:7], v2, off offset:192
	s_branch .LBB0_1473
